# peer_act: u-row scale table staged in LDS per block (gathers become LDS reads), register-staged 2-3 deep prefetch of partial-hidden slices / indices / gates
# baseline (speedup 1.0000x reference)
.LBB0_654:
	s_or_b64 exec, exec, s[2:3]
	s_add_u32 s48, s94, 0x3a700000
	s_addc_u32 s49, s95, 0
	s_add_u32 s50, s94, 0x3a710000
	s_addc_u32 s51, s95, 0
	s_lshl_b64 s[2:3], s[88:89], 10
	v_mov_b32_e32 v163, 0
	s_mov_b32 s97, 0
	v_lshl_add_u64 v[184:185], s[2:3], 0, v[162:163]
	s_mov_b64 s[2:3], 0x810000
	s_lshl_b64 s[52:53], s[96:97], 10
	v_cmp_gt_u64_e64 s[14:15], s[2:3], v[184:185]
	s_barrier
	s_and_saveexec_b64 s[2:3], s[14:15]
	s_cbranch_execz .LBB0_673
	s_add_u32 s24, s94, 0x3a700000
	s_addc_u32 s25, s95, 0
	s_add_u32 s26, s94, 0x3a710000
	s_addc_u32 s27, s95, 0
	v_lshlrev_b32_e32 v251, 4, v156
	v_add_u32_e32 v244, 0x0, v251
	global_load_dwordx4 v[0:3], v244, s[24:25]
	v_add_u32_e32 v244, 0x1000, v251
	global_load_dwordx4 v[4:7], v244, s[24:25]
	v_add_u32_e32 v244, 0x2000, v251
	global_load_dwordx4 v[8:11], v244, s[24:25]
	v_add_u32_e32 v244, 0x3000, v251
	global_load_dwordx4 v[12:15], v244, s[24:25]
	v_add_u32_e32 v244, 0x4000, v251
	global_load_dwordx4 v[16:19], v244, s[24:25]
	v_add_u32_e32 v244, 0x5000, v251
	global_load_dwordx4 v[20:23], v244, s[24:25]
	v_add_u32_e32 v244, 0x6000, v251
	global_load_dwordx4 v[24:27], v244, s[24:25]
	v_add_u32_e32 v244, 0x7000, v251
	global_load_dwordx4 v[28:31], v244, s[24:25]
	s_waitcnt vmcnt(0)
	ds_write_b128 v251, v[0:3] offset:0
	ds_write_b128 v251, v[4:7] offset:4096
	ds_write_b128 v251, v[8:11] offset:8192
	ds_write_b128 v251, v[12:15] offset:12288
	ds_write_b128 v251, v[16:19] offset:16384
	ds_write_b128 v251, v[20:23] offset:20480
	ds_write_b128 v251, v[24:27] offset:24576
	ds_write_b128 v251, v[28:31] offset:28672
	v_add_u32_e32 v244, 0x8000, v251
	global_load_dwordx4 v[0:3], v244, s[24:25]
	v_add_u32_e32 v244, 0x9000, v251
	global_load_dwordx4 v[4:7], v244, s[24:25]
	v_add_u32_e32 v244, 0xa000, v251
	global_load_dwordx4 v[8:11], v244, s[24:25]
	v_add_u32_e32 v244, 0xb000, v251
	global_load_dwordx4 v[12:15], v244, s[24:25]
	v_add_u32_e32 v244, 0xc000, v251
	global_load_dwordx4 v[16:19], v244, s[24:25]
	v_add_u32_e32 v244, 0xd000, v251
	global_load_dwordx4 v[20:23], v244, s[24:25]
	v_add_u32_e32 v244, 0xe000, v251
	global_load_dwordx4 v[24:27], v244, s[24:25]
	v_add_u32_e32 v244, 0xf000, v251
	global_load_dwordx4 v[28:31], v244, s[24:25]
	s_waitcnt vmcnt(0)
	ds_write_b128 v251, v[0:3] offset:32768
	ds_write_b128 v251, v[4:7] offset:36864
	ds_write_b128 v251, v[8:11] offset:40960
	ds_write_b128 v251, v[12:15] offset:45056
	ds_write_b128 v251, v[16:19] offset:49152
	ds_write_b128 v251, v[20:23] offset:53248
	ds_write_b128 v251, v[24:27] offset:57344
	ds_write_b128 v251, v[28:31] offset:61440
	s_waitcnt lgkmcnt(0)
	s_barrier
	s_mov_b32 s16, 16
	s_cmp_lt_u32 s88, 64
	s_cselect_b32 s16, 17, 16
	s_lshl_b32 s4, s88, 12
	v_lshlrev_b32_e32 v244, 4, v156
	v_add_u32_e32 v244, s4, v244
	s_sub_u32 s4, s16, 1
	s_lshl_b32 s4, s4, 21
	v_add_u32_e32 v245, s4, v244
	v_add_u32_e32 v249, 0x1a340000, v245
	v_add_u32_e32 v247, 0x18300000, v245
	v_add_u32_e32 v245, 0x8100000, v245
	v_add_u32_e32 v248, 0x1a340000, v244
	v_mov_b32_e32 v250, v248
	v_add_u32_e32 v246, 0x18300000, v244
	v_add_u32_e32 v244, 0x8100000, v244
	v_mov_b32_e32 v187, 0x378e98ab
	v_mov_b32_e32 v188, 0xb9c68948
	v_mov_b32_e32 v189, 0x3b7cd369
	v_mov_b32_e32 v190, 0xbcc618b2
	v_mov_b32_e32 v191, 0x3dda74e4
	v_mov_b32_e32 v192, 0x3f228afd
	v_mov_b32_e32 v193, 0x3e03c728
	v_mov_b32_e32 v194, 0x7f800000
	v_mov_b32_e32 v195, 0x3ba10414
	s_mov_b32 s19, 0xbfb8aa3b
	s_mov_b32 s20, 0x42ce8ed0
	s_mov_b32 s21, 0xc2b17218
	s_brev_b32 s22, -2
	global_load_dwordx4 v[96:99], v246, s[94:95]
	v_add_u32_e32 v246, 0x200000, v246
	v_min_u32_e32 v246, v246, v247
	global_load_dwordx4 v[100:103], v246, s[94:95]
	v_add_u32_e32 v246, 0x200000, v246
	v_min_u32_e32 v246, v246, v247
	global_load_dwordx4 v[104:107], v246, s[94:95]
	v_add_u32_e32 v246, 0x200000, v246
	v_min_u32_e32 v246, v246, v247
	global_load_dwordx4 v[0:3], v244, s[94:95]
	v_add_u32_e32 v251, 0x2040000, v244
	global_load_dwordx4 v[4:7], v251, s[94:95]
	v_add_u32_e32 v251, 0x4080000, v244
	global_load_dwordx4 v[8:11], v251, s[94:95]
	v_add_u32_e32 v251, 0x60c0000, v244
	global_load_dwordx4 v[12:15], v251, s[94:95]
	v_add_u32_e32 v251, 0x8100000, v244
	global_load_dwordx4 v[16:19], v251, s[94:95]
	v_add_u32_e32 v251, 0xa140000, v244
	global_load_dwordx4 v[20:23], v251, s[94:95]
	v_add_u32_e32 v251, 0xc180000, v244
	global_load_dwordx4 v[24:27], v251, s[94:95]
	v_add_u32_e32 v251, 0xe1c0000, v244
	global_load_dwordx4 v[28:31], v251, s[94:95]
	v_add_u32_e32 v244, 0x200000, v244
	v_min_u32_e32 v244, v244, v245
	global_load_dwordx4 v[32:35], v244, s[94:95]
	v_add_u32_e32 v251, 0x2040000, v244
	global_load_dwordx4 v[36:39], v251, s[94:95]
	v_add_u32_e32 v251, 0x4080000, v244
	global_load_dwordx4 v[40:43], v251, s[94:95]
	v_add_u32_e32 v251, 0x60c0000, v244
	global_load_dwordx4 v[44:47], v251, s[94:95]
	v_add_u32_e32 v251, 0x8100000, v244
	global_load_dwordx4 v[48:51], v251, s[94:95]
	v_add_u32_e32 v251, 0xa140000, v244
	global_load_dwordx4 v[52:55], v251, s[94:95]
	v_add_u32_e32 v251, 0xc180000, v244
	global_load_dwordx4 v[56:59], v251, s[94:95]
	v_add_u32_e32 v251, 0xe1c0000, v244
	global_load_dwordx4 v[60:63], v251, s[94:95]
	v_add_u32_e32 v244, 0x200000, v244
	v_min_u32_e32 v244, v244, v245
	s_waitcnt vmcnt(18)
	v_lshlrev_b32_e32 v196, 2, v96
	v_lshlrev_b32_e32 v197, 2, v97
	v_lshlrev_b32_e32 v198, 2, v98
	v_lshlrev_b32_e32 v199, 2, v99
	ds_read_b32 v112, v196
	ds_read_b32 v113, v197
	ds_read_b32 v114, v198
	ds_read_b32 v115, v199
	global_load_dword v120, v196, s[26:27]
	global_load_dword v121, v197, s[26:27]
	global_load_dword v122, v198, s[26:27]
	global_load_dword v123, v199, s[26:27]
	global_load_dwordx4 v[128:131], v248, s[94:95]
	v_add_u32_e32 v248, 0x200000, v248
	v_min_u32_e32 v248, v248, v249
	s_waitcnt vmcnt(5)
	global_load_dword v200, v250, s[94:95]
	global_load_dword v200, v250, s[94:95]
	global_load_dword v200, v250, s[94:95]
	global_load_dword v200, v250, s[94:95]
	global_load_dword v200, v250, s[94:95]
	global_load_dword v200, v250, s[94:95]
	global_load_dword v200, v250, s[94:95]
	global_load_dword v200, v250, s[94:95]
	global_load_dword v200, v250, s[94:95]
	global_load_dword v200, v250, s[94:95]
	s_mov_b32 s17, 0
.Lact0_loop:
	s_waitcnt vmcnt(24)
	v_lshlrev_b32_e32 v196, 2, v100
	v_lshlrev_b32_e32 v197, 2, v101
	v_lshlrev_b32_e32 v198, 2, v102
	v_lshlrev_b32_e32 v199, 2, v103
	ds_read_b32 v116, v196
	ds_read_b32 v117, v197
	ds_read_b32 v118, v198
	ds_read_b32 v119, v199
	global_load_dword v124, v196, s[26:27]
	global_load_dword v125, v197, s[26:27]
	global_load_dword v126, v198, s[26:27]
	global_load_dword v127, v199, s[26:27]
	global_load_dwordx4 v[132:135], v248, s[94:95]
	v_add_u32_e32 v248, 0x200000, v248
	v_min_u32_e32 v248, v248, v249
	global_load_dwordx4 v[108:111], v246, s[94:95]
	v_add_u32_e32 v246, 0x200000, v246
	v_min_u32_e32 v246, v246, v247
	global_load_dwordx4 v[64:67], v244, s[94:95]
	v_add_u32_e32 v251, 0x2040000, v244
	global_load_dwordx4 v[68:71], v251, s[94:95]
	v_add_u32_e32 v251, 0x4080000, v244
	global_load_dwordx4 v[72:75], v251, s[94:95]
	v_add_u32_e32 v251, 0x60c0000, v244
	global_load_dwordx4 v[76:79], v251, s[94:95]
	v_add_u32_e32 v251, 0x8100000, v244
	global_load_dwordx4 v[80:83], v251, s[94:95]
	v_add_u32_e32 v251, 0xa140000, v244
	global_load_dwordx4 v[84:87], v251, s[94:95]
	v_add_u32_e32 v251, 0xc180000, v244
	global_load_dwordx4 v[88:91], v251, s[94:95]
	v_add_u32_e32 v251, 0xe1c0000, v244
	global_load_dwordx4 v[92:95], v251, s[94:95]
	v_add_u32_e32 v244, 0x200000, v244
	v_min_u32_e32 v244, v244, v245
	s_waitcnt vmcnt(24) lgkmcnt(4)
	v_add_f32_e32 v212, 0, v0
	v_add_f32_e32 v219, 0, v1
	v_add_f32_e32 v226, 0, v2
	v_add_f32_e32 v233, 0, v3
	v_add_f32_e32 v212, v212, v4
	v_add_f32_e32 v219, v219, v5
	v_add_f32_e32 v226, v226, v6
	v_add_f32_e32 v233, v233, v7
	v_add_f32_e32 v212, v212, v8
	v_add_f32_e32 v219, v219, v9
	v_add_f32_e32 v226, v226, v10
	v_add_f32_e32 v233, v233, v11
	v_add_f32_e32 v212, v212, v12
	v_add_f32_e32 v219, v219, v13
	v_add_f32_e32 v226, v226, v14
	v_add_f32_e32 v233, v233, v15
	v_add_f32_e32 v212, v212, v16
	v_add_f32_e32 v219, v219, v17
	v_add_f32_e32 v226, v226, v18
	v_add_f32_e32 v233, v233, v19
	v_add_f32_e32 v212, v212, v20
	v_add_f32_e32 v219, v219, v21
	v_add_f32_e32 v226, v226, v22
	v_add_f32_e32 v233, v233, v23
	v_add_f32_e32 v212, v212, v24
	v_add_f32_e32 v219, v219, v25
	v_add_f32_e32 v226, v226, v26
	v_add_f32_e32 v233, v233, v27
	v_add_f32_e32 v212, v212, v28
	v_add_f32_e32 v219, v219, v29
	v_add_f32_e32 v226, v226, v30
	v_add_f32_e32 v233, v233, v31
	v_mul_f32_e32 v212, v212, v112
	v_mul_f32_e32 v219, v219, v113
	v_mul_f32_e32 v226, v226, v114
	v_mul_f32_e32 v233, v233, v115
	v_mul_f32_e32 v213, 0x3f3504f3, v212
	v_mul_f32_e32 v220, 0x3f3504f3, v219
	v_mul_f32_e32 v227, 0x3f3504f3, v226
	v_mul_f32_e32 v234, 0x3f3504f3, v233
	v_fma_f32 v214, |v213|, v187, v188
	v_fma_f32 v221, |v220|, v187, v188
	v_fma_f32 v228, |v227|, v187, v188
	v_fma_f32 v235, |v234|, v187, v188
	v_fma_f32 v214, |v213|, v214, v189
	v_fma_f32 v221, |v220|, v221, v189
	v_fma_f32 v228, |v227|, v228, v189
	v_fma_f32 v235, |v234|, v235, v189
	v_fma_f32 v214, |v213|, v214, v190
	v_fma_f32 v221, |v220|, v221, v190
	v_fma_f32 v228, |v227|, v228, v190
	v_fma_f32 v235, |v234|, v235, v190
	v_fma_f32 v214, |v213|, v214, v191
	v_fma_f32 v221, |v220|, v221, v191
	v_fma_f32 v228, |v227|, v228, v191
	v_fma_f32 v235, |v234|, v235, v191
	v_fma_f32 v214, |v213|, v214, v192
	v_fma_f32 v221, |v220|, v221, v192
	v_fma_f32 v228, |v227|, v228, v192
	v_fma_f32 v235, |v234|, v235, v192
	v_fma_f32 v214, |v213|, v214, v193
	v_fma_f32 v221, |v220|, v221, v193
	v_fma_f32 v228, |v227|, v228, v193
	v_fma_f32 v235, |v234|, v235, v193
	v_fma_f32 v214, |v213|, v214, |v213|
	v_fma_f32 v221, |v220|, v221, |v220|
	v_fma_f32 v228, |v227|, v228, |v227|
	v_fma_f32 v235, |v234|, v235, |v234|
	v_mul_f32_e32 v216, s19, v214
	v_mul_f32_e32 v223, s19, v221
	v_mul_f32_e32 v230, s19, v228
	v_mul_f32_e32 v237, s19, v235
	v_fma_f32 v217, v214, s19, -v216
	v_fma_f32 v224, v221, s19, -v223
	v_fma_f32 v231, v228, s19, -v230
	v_fma_f32 v238, v235, s19, -v237
	v_rndne_f32_e32 v218, v216
	v_rndne_f32_e32 v225, v223
	v_rndne_f32_e32 v232, v230
	v_rndne_f32_e32 v239, v237
	v_fmac_f32_e32 v217, 0xb2a5705f, v214
	v_fmac_f32_e32 v224, 0xb2a5705f, v221
	v_fmac_f32_e32 v231, 0xb2a5705f, v228
	v_fmac_f32_e32 v238, 0xb2a5705f, v235
	v_sub_f32_e32 v216, v216, v218
	v_sub_f32_e32 v223, v223, v225
	v_sub_f32_e32 v230, v230, v232
	v_sub_f32_e32 v237, v237, v239
	v_add_f32_e32 v216, v216, v217
	v_add_f32_e32 v223, v223, v224
	v_add_f32_e32 v230, v230, v231
	v_add_f32_e32 v237, v237, v238
	v_cvt_i32_f32_e32 v218, v218
	v_cvt_i32_f32_e32 v225, v225
	v_cvt_i32_f32_e32 v232, v232
	v_cvt_i32_f32_e32 v239, v239
	v_exp_f32_e32 v216, v216
	v_exp_f32_e32 v223, v223
	v_exp_f32_e32 v230, v230
	v_exp_f32_e32 v237, v237
	v_cmp_nlt_f32_e64 s[4:5], s20, v214
	v_cmp_nlt_f32_e64 s[98:99], s20, v221
	v_cmp_nlt_f32_e64 s[100:101], s20, v228
	v_cmp_nlt_f32_e64 vcc, s20, v235
	v_ldexp_f32 v216, v216, v218
	v_ldexp_f32 v223, v223, v225
	v_ldexp_f32 v230, v230, v232
	v_ldexp_f32 v237, v237, v239
	v_mul_f32_e32 v215, v213, v213
	v_mul_f32_e32 v222, v220, v220
	v_mul_f32_e32 v229, v227, v227
	v_mul_f32_e32 v236, v234, v234
	v_cndmask_b32_e64 v216, 0, v216, s[4:5]
	v_cndmask_b32_e64 v223, 0, v223, s[98:99]
	v_cndmask_b32_e64 v230, 0, v230, s[100:101]
	v_cndmask_b32_e64 v237, 0, v237, vcc
	v_cmp_ngt_f32_e64 s[4:5], s21, v214
	v_cmp_ngt_f32_e64 s[98:99], s21, v221
	v_cmp_ngt_f32_e64 s[100:101], s21, v228
	v_cmp_ngt_f32_e64 vcc, s21, v235
	v_fmamk_f32 v217, v215, 0xba1345e1, v195
	v_fmamk_f32 v224, v222, 0xba1345e1, v195
	v_fmamk_f32 v231, v229, 0xba1345e1, v195
	v_fmamk_f32 v238, v236, 0xba1345e1, v195
	v_fmaak_f32 v217, v215, v217, 0xbcdac9b8
	v_fmaak_f32 v224, v222, v224, 0xbcdac9b8
	v_fmaak_f32 v231, v229, v231, 0xbcdac9b8
	v_fmaak_f32 v238, v236, v238, 0xbcdac9b8
	v_cndmask_b32_e64 v216, v194, v216, s[4:5]
	v_cndmask_b32_e64 v223, v194, v223, s[98:99]
	v_cndmask_b32_e64 v230, v194, v230, s[100:101]
	v_cndmask_b32_e64 v237, v194, v237, vcc
	v_fmaak_f32 v217, v215, v217, 0x3de703be
	v_fmaak_f32 v224, v222, v224, 0x3de703be
	v_fmaak_f32 v231, v229, v231, 0x3de703be
	v_fmaak_f32 v238, v236, v238, 0x3de703be
	v_fmaak_f32 v217, v215, v217, 0xbec09330
	v_fmaak_f32 v224, v222, v224, 0xbec09330
	v_fmaak_f32 v231, v229, v231, 0xbec09330
	v_fmaak_f32 v238, v236, v238, 0xbec09330
	v_sub_f32_e32 v216, 1.0, v216
	v_sub_f32_e32 v223, 1.0, v223
	v_sub_f32_e32 v230, 1.0, v230
	v_sub_f32_e32 v237, 1.0, v237
	v_fmaak_f32 v217, v215, v217, 0x3e0375d0
	v_fmaak_f32 v224, v222, v224, 0x3e0375d0
	v_fmaak_f32 v231, v229, v231, 0x3e0375d0
	v_fmaak_f32 v238, v236, v238, 0x3e0375d0
	v_cmp_nlt_f32_e64 s[4:5], |v213|, 1.0
	v_cmp_nlt_f32_e64 s[98:99], |v220|, 1.0
	v_cmp_nlt_f32_e64 s[100:101], |v227|, 1.0
	v_cmp_nlt_f32_e64 vcc, |v234|, 1.0
	v_fma_f32 v217, |v213|, v217, |v213|
	v_fma_f32 v224, |v220|, v224, |v220|
	v_fma_f32 v231, |v227|, v231, |v227|
	v_fma_f32 v238, |v234|, v238, |v234|
	v_mul_f32_e32 v212, 0.5, v212
	v_mul_f32_e32 v219, 0.5, v219
	v_mul_f32_e32 v226, 0.5, v226
	v_mul_f32_e32 v233, 0.5, v233
	v_mul_f32_e32 v215, v128, v120
	v_mul_f32_e32 v222, v129, v121
	v_mul_f32_e32 v229, v130, v122
	v_mul_f32_e32 v236, v131, v123
	v_cndmask_b32_e64 v216, v217, v216, s[4:5]
	v_cndmask_b32_e64 v223, v224, v223, s[98:99]
	v_cndmask_b32_e64 v230, v231, v230, s[100:101]
	v_cndmask_b32_e64 v237, v238, v237, vcc
	v_bfi_b32 v216, s22, v216, v213
	v_bfi_b32 v223, s22, v223, v220
	v_bfi_b32 v230, s22, v230, v227
	v_bfi_b32 v237, s22, v237, v234
	v_add_f32_e32 v216, 1.0, v216
	v_add_f32_e32 v223, 1.0, v223
	v_add_f32_e32 v230, 1.0, v230
	v_add_f32_e32 v237, 1.0, v237
	v_mul_f32_e32 v212, v212, v216
	v_mul_f32_e32 v219, v219, v223
	v_mul_f32_e32 v226, v226, v230
	v_mul_f32_e32 v233, v233, v237
	v_mul_f32_e32 v212, v128, v212
	v_mul_f32_e32 v219, v129, v219
	v_mul_f32_e32 v226, v130, v226
	v_mul_f32_e32 v233, v131, v233
	v_mul_f32_e32 v240, v120, v212
	v_mul_f32_e32 v241, v121, v219
	v_mul_f32_e32 v242, v122, v226
	v_mul_f32_e32 v243, v123, v233
	global_store_dwordx4 v250, v[240:243], s[94:95]
	v_add_u32_e32 v250, 0x200000, v250
	s_add_u32 s17, s17, 1
	s_cmp_lt_u32 s17, s16
	s_cbranch_scc0 .Lact0_done
	s_waitcnt vmcnt(24)
	v_lshlrev_b32_e32 v196, 2, v104
	v_lshlrev_b32_e32 v197, 2, v105
	v_lshlrev_b32_e32 v198, 2, v106
	v_lshlrev_b32_e32 v199, 2, v107
	ds_read_b32 v112, v196
	ds_read_b32 v113, v197
	ds_read_b32 v114, v198
	ds_read_b32 v115, v199
	global_load_dword v120, v196, s[26:27]
	global_load_dword v121, v197, s[26:27]
	global_load_dword v122, v198, s[26:27]
	global_load_dword v123, v199, s[26:27]
	global_load_dwordx4 v[128:131], v248, s[94:95]
	v_add_u32_e32 v248, 0x200000, v248
	v_min_u32_e32 v248, v248, v249
	global_load_dwordx4 v[96:99], v246, s[94:95]
	v_add_u32_e32 v246, 0x200000, v246
	v_min_u32_e32 v246, v246, v247
	global_load_dwordx4 v[0:3], v244, s[94:95]
	v_add_u32_e32 v251, 0x2040000, v244
	global_load_dwordx4 v[4:7], v251, s[94:95]
	v_add_u32_e32 v251, 0x4080000, v244
	global_load_dwordx4 v[8:11], v251, s[94:95]
	v_add_u32_e32 v251, 0x60c0000, v244
	global_load_dwordx4 v[12:15], v251, s[94:95]
	v_add_u32_e32 v251, 0x8100000, v244
	global_load_dwordx4 v[16:19], v251, s[94:95]
	v_add_u32_e32 v251, 0xa140000, v244
	global_load_dwordx4 v[20:23], v251, s[94:95]
	v_add_u32_e32 v251, 0xc180000, v244
	global_load_dwordx4 v[24:27], v251, s[94:95]
	v_add_u32_e32 v251, 0xe1c0000, v244
	global_load_dwordx4 v[28:31], v251, s[94:95]
	v_add_u32_e32 v244, 0x200000, v244
	v_min_u32_e32 v244, v244, v245
	s_waitcnt vmcnt(24) lgkmcnt(4)
	v_add_f32_e32 v212, 0, v32
	v_add_f32_e32 v219, 0, v33
	v_add_f32_e32 v226, 0, v34
	v_add_f32_e32 v233, 0, v35
	v_add_f32_e32 v212, v212, v36
	v_add_f32_e32 v219, v219, v37
	v_add_f32_e32 v226, v226, v38
	v_add_f32_e32 v233, v233, v39
	v_add_f32_e32 v212, v212, v40
	v_add_f32_e32 v219, v219, v41
	v_add_f32_e32 v226, v226, v42
	v_add_f32_e32 v233, v233, v43
	v_add_f32_e32 v212, v212, v44
	v_add_f32_e32 v219, v219, v45
	v_add_f32_e32 v226, v226, v46
	v_add_f32_e32 v233, v233, v47
	v_add_f32_e32 v212, v212, v48
	v_add_f32_e32 v219, v219, v49
	v_add_f32_e32 v226, v226, v50
	v_add_f32_e32 v233, v233, v51
	v_add_f32_e32 v212, v212, v52
	v_add_f32_e32 v219, v219, v53
	v_add_f32_e32 v226, v226, v54
	v_add_f32_e32 v233, v233, v55
	v_add_f32_e32 v212, v212, v56
	v_add_f32_e32 v219, v219, v57
	v_add_f32_e32 v226, v226, v58
	v_add_f32_e32 v233, v233, v59
	v_add_f32_e32 v212, v212, v60
	v_add_f32_e32 v219, v219, v61
	v_add_f32_e32 v226, v226, v62
	v_add_f32_e32 v233, v233, v63
	v_mul_f32_e32 v212, v212, v116
	v_mul_f32_e32 v219, v219, v117
	v_mul_f32_e32 v226, v226, v118
	v_mul_f32_e32 v233, v233, v119
	v_mul_f32_e32 v213, 0x3f3504f3, v212
	v_mul_f32_e32 v220, 0x3f3504f3, v219
	v_mul_f32_e32 v227, 0x3f3504f3, v226
	v_mul_f32_e32 v234, 0x3f3504f3, v233
	v_fma_f32 v214, |v213|, v187, v188
	v_fma_f32 v221, |v220|, v187, v188
	v_fma_f32 v228, |v227|, v187, v188
	v_fma_f32 v235, |v234|, v187, v188
	v_fma_f32 v214, |v213|, v214, v189
	v_fma_f32 v221, |v220|, v221, v189
	v_fma_f32 v228, |v227|, v228, v189
	v_fma_f32 v235, |v234|, v235, v189
	v_fma_f32 v214, |v213|, v214, v190
	v_fma_f32 v221, |v220|, v221, v190
	v_fma_f32 v228, |v227|, v228, v190
	v_fma_f32 v235, |v234|, v235, v190
	v_fma_f32 v214, |v213|, v214, v191
	v_fma_f32 v221, |v220|, v221, v191
	v_fma_f32 v228, |v227|, v228, v191
	v_fma_f32 v235, |v234|, v235, v191
	v_fma_f32 v214, |v213|, v214, v192
	v_fma_f32 v221, |v220|, v221, v192
	v_fma_f32 v228, |v227|, v228, v192
	v_fma_f32 v235, |v234|, v235, v192
	v_fma_f32 v214, |v213|, v214, v193
	v_fma_f32 v221, |v220|, v221, v193
	v_fma_f32 v228, |v227|, v228, v193
	v_fma_f32 v235, |v234|, v235, v193
	v_fma_f32 v214, |v213|, v214, |v213|
	v_fma_f32 v221, |v220|, v221, |v220|
	v_fma_f32 v228, |v227|, v228, |v227|
	v_fma_f32 v235, |v234|, v235, |v234|
	v_mul_f32_e32 v216, s19, v214
	v_mul_f32_e32 v223, s19, v221
	v_mul_f32_e32 v230, s19, v228
	v_mul_f32_e32 v237, s19, v235
	v_fma_f32 v217, v214, s19, -v216
	v_fma_f32 v224, v221, s19, -v223
	v_fma_f32 v231, v228, s19, -v230
	v_fma_f32 v238, v235, s19, -v237
	v_rndne_f32_e32 v218, v216
	v_rndne_f32_e32 v225, v223
	v_rndne_f32_e32 v232, v230
	v_rndne_f32_e32 v239, v237
	v_fmac_f32_e32 v217, 0xb2a5705f, v214
	v_fmac_f32_e32 v224, 0xb2a5705f, v221
	v_fmac_f32_e32 v231, 0xb2a5705f, v228
	v_fmac_f32_e32 v238, 0xb2a5705f, v235
	v_sub_f32_e32 v216, v216, v218
	v_sub_f32_e32 v223, v223, v225
	v_sub_f32_e32 v230, v230, v232
	v_sub_f32_e32 v237, v237, v239
	v_add_f32_e32 v216, v216, v217
	v_add_f32_e32 v223, v223, v224
	v_add_f32_e32 v230, v230, v231
	v_add_f32_e32 v237, v237, v238
	v_cvt_i32_f32_e32 v218, v218
	v_cvt_i32_f32_e32 v225, v225
	v_cvt_i32_f32_e32 v232, v232
	v_cvt_i32_f32_e32 v239, v239
	v_exp_f32_e32 v216, v216
	v_exp_f32_e32 v223, v223
	v_exp_f32_e32 v230, v230
	v_exp_f32_e32 v237, v237
	v_cmp_nlt_f32_e64 s[4:5], s20, v214
	v_cmp_nlt_f32_e64 s[98:99], s20, v221
	v_cmp_nlt_f32_e64 s[100:101], s20, v228
	v_cmp_nlt_f32_e64 vcc, s20, v235
	v_ldexp_f32 v216, v216, v218
	v_ldexp_f32 v223, v223, v225
	v_ldexp_f32 v230, v230, v232
	v_ldexp_f32 v237, v237, v239
	v_mul_f32_e32 v215, v213, v213
	v_mul_f32_e32 v222, v220, v220
	v_mul_f32_e32 v229, v227, v227
	v_mul_f32_e32 v236, v234, v234
	v_cndmask_b32_e64 v216, 0, v216, s[4:5]
	v_cndmask_b32_e64 v223, 0, v223, s[98:99]
	v_cndmask_b32_e64 v230, 0, v230, s[100:101]
	v_cndmask_b32_e64 v237, 0, v237, vcc
	v_cmp_ngt_f32_e64 s[4:5], s21, v214
	v_cmp_ngt_f32_e64 s[98:99], s21, v221
	v_cmp_ngt_f32_e64 s[100:101], s21, v228
	v_cmp_ngt_f32_e64 vcc, s21, v235
	v_fmamk_f32 v217, v215, 0xba1345e1, v195
	v_fmamk_f32 v224, v222, 0xba1345e1, v195
	v_fmamk_f32 v231, v229, 0xba1345e1, v195
	v_fmamk_f32 v238, v236, 0xba1345e1, v195
	v_fmaak_f32 v217, v215, v217, 0xbcdac9b8
	v_fmaak_f32 v224, v222, v224, 0xbcdac9b8
	v_fmaak_f32 v231, v229, v231, 0xbcdac9b8
	v_fmaak_f32 v238, v236, v238, 0xbcdac9b8
	v_cndmask_b32_e64 v216, v194, v216, s[4:5]
	v_cndmask_b32_e64 v223, v194, v223, s[98:99]
	v_cndmask_b32_e64 v230, v194, v230, s[100:101]
	v_cndmask_b32_e64 v237, v194, v237, vcc
	v_fmaak_f32 v217, v215, v217, 0x3de703be
	v_fmaak_f32 v224, v222, v224, 0x3de703be
	v_fmaak_f32 v231, v229, v231, 0x3de703be
	v_fmaak_f32 v238, v236, v238, 0x3de703be
	v_fmaak_f32 v217, v215, v217, 0xbec09330
	v_fmaak_f32 v224, v222, v224, 0xbec09330
	v_fmaak_f32 v231, v229, v231, 0xbec09330
	v_fmaak_f32 v238, v236, v238, 0xbec09330
	v_sub_f32_e32 v216, 1.0, v216
	v_sub_f32_e32 v223, 1.0, v223
	v_sub_f32_e32 v230, 1.0, v230
	v_sub_f32_e32 v237, 1.0, v237
	v_fmaak_f32 v217, v215, v217, 0x3e0375d0
	v_fmaak_f32 v224, v222, v224, 0x3e0375d0
	v_fmaak_f32 v231, v229, v231, 0x3e0375d0
	v_fmaak_f32 v238, v236, v238, 0x3e0375d0
	v_cmp_nlt_f32_e64 s[4:5], |v213|, 1.0
	v_cmp_nlt_f32_e64 s[98:99], |v220|, 1.0
	v_cmp_nlt_f32_e64 s[100:101], |v227|, 1.0
	v_cmp_nlt_f32_e64 vcc, |v234|, 1.0
	v_fma_f32 v217, |v213|, v217, |v213|
	v_fma_f32 v224, |v220|, v224, |v220|
	v_fma_f32 v231, |v227|, v231, |v227|
	v_fma_f32 v238, |v234|, v238, |v234|
	v_mul_f32_e32 v212, 0.5, v212
	v_mul_f32_e32 v219, 0.5, v219
	v_mul_f32_e32 v226, 0.5, v226
	v_mul_f32_e32 v233, 0.5, v233
	v_mul_f32_e32 v215, v132, v124
	v_mul_f32_e32 v222, v133, v125
	v_mul_f32_e32 v229, v134, v126
	v_mul_f32_e32 v236, v135, v127
	v_cndmask_b32_e64 v216, v217, v216, s[4:5]
	v_cndmask_b32_e64 v223, v224, v223, s[98:99]
	v_cndmask_b32_e64 v230, v231, v230, s[100:101]
	v_cndmask_b32_e64 v237, v238, v237, vcc
	v_bfi_b32 v216, s22, v216, v213
	v_bfi_b32 v223, s22, v223, v220
	v_bfi_b32 v230, s22, v230, v227
	v_bfi_b32 v237, s22, v237, v234
	v_add_f32_e32 v216, 1.0, v216
	v_add_f32_e32 v223, 1.0, v223
	v_add_f32_e32 v230, 1.0, v230
	v_add_f32_e32 v237, 1.0, v237
	v_mul_f32_e32 v212, v212, v216
	v_mul_f32_e32 v219, v219, v223
	v_mul_f32_e32 v226, v226, v230
	v_mul_f32_e32 v233, v233, v237
	v_mul_f32_e32 v212, v132, v212
	v_mul_f32_e32 v219, v133, v219
	v_mul_f32_e32 v226, v134, v226
	v_mul_f32_e32 v233, v135, v233
	v_mul_f32_e32 v240, v124, v212
	v_mul_f32_e32 v241, v125, v219
	v_mul_f32_e32 v242, v126, v226
	v_mul_f32_e32 v243, v127, v233
	global_store_dwordx4 v250, v[240:243], s[94:95]
	v_add_u32_e32 v250, 0x200000, v250
	s_add_u32 s17, s17, 1
	s_cmp_lt_u32 s17, s16
	s_cbranch_scc0 .Lact0_done
	s_waitcnt vmcnt(24)
	v_lshlrev_b32_e32 v196, 2, v108
	v_lshlrev_b32_e32 v197, 2, v109
	v_lshlrev_b32_e32 v198, 2, v110
	v_lshlrev_b32_e32 v199, 2, v111
	ds_read_b32 v116, v196
	ds_read_b32 v117, v197
	ds_read_b32 v118, v198
	ds_read_b32 v119, v199
	global_load_dword v124, v196, s[26:27]
	global_load_dword v125, v197, s[26:27]
	global_load_dword v126, v198, s[26:27]
	global_load_dword v127, v199, s[26:27]
	global_load_dwordx4 v[132:135], v248, s[94:95]
	v_add_u32_e32 v248, 0x200000, v248
	v_min_u32_e32 v248, v248, v249
	global_load_dwordx4 v[100:103], v246, s[94:95]
	v_add_u32_e32 v246, 0x200000, v246
	v_min_u32_e32 v246, v246, v247
	global_load_dwordx4 v[32:35], v244, s[94:95]
	v_add_u32_e32 v251, 0x2040000, v244
	global_load_dwordx4 v[36:39], v251, s[94:95]
	v_add_u32_e32 v251, 0x4080000, v244
	global_load_dwordx4 v[40:43], v251, s[94:95]
	v_add_u32_e32 v251, 0x60c0000, v244
	global_load_dwordx4 v[44:47], v251, s[94:95]
	v_add_u32_e32 v251, 0x8100000, v244
	global_load_dwordx4 v[48:51], v251, s[94:95]
	v_add_u32_e32 v251, 0xa140000, v244
	global_load_dwordx4 v[52:55], v251, s[94:95]
	v_add_u32_e32 v251, 0xc180000, v244
	global_load_dwordx4 v[56:59], v251, s[94:95]
	v_add_u32_e32 v251, 0xe1c0000, v244
	global_load_dwordx4 v[60:63], v251, s[94:95]
	v_add_u32_e32 v244, 0x200000, v244
	v_min_u32_e32 v244, v244, v245
	s_waitcnt vmcnt(24) lgkmcnt(4)
	v_add_f32_e32 v212, 0, v64
	v_add_f32_e32 v219, 0, v65
	v_add_f32_e32 v226, 0, v66
	v_add_f32_e32 v233, 0, v67
	v_add_f32_e32 v212, v212, v68
	v_add_f32_e32 v219, v219, v69
	v_add_f32_e32 v226, v226, v70
	v_add_f32_e32 v233, v233, v71
	v_add_f32_e32 v212, v212, v72
	v_add_f32_e32 v219, v219, v73
	v_add_f32_e32 v226, v226, v74
	v_add_f32_e32 v233, v233, v75
	v_add_f32_e32 v212, v212, v76
	v_add_f32_e32 v219, v219, v77
	v_add_f32_e32 v226, v226, v78
	v_add_f32_e32 v233, v233, v79
	v_add_f32_e32 v212, v212, v80
	v_add_f32_e32 v219, v219, v81
	v_add_f32_e32 v226, v226, v82
	v_add_f32_e32 v233, v233, v83
	v_add_f32_e32 v212, v212, v84
	v_add_f32_e32 v219, v219, v85
	v_add_f32_e32 v226, v226, v86
	v_add_f32_e32 v233, v233, v87
	v_add_f32_e32 v212, v212, v88
	v_add_f32_e32 v219, v219, v89
	v_add_f32_e32 v226, v226, v90
	v_add_f32_e32 v233, v233, v91
	v_add_f32_e32 v212, v212, v92
	v_add_f32_e32 v219, v219, v93
	v_add_f32_e32 v226, v226, v94
	v_add_f32_e32 v233, v233, v95
	v_mul_f32_e32 v212, v212, v112
	v_mul_f32_e32 v219, v219, v113
	v_mul_f32_e32 v226, v226, v114
	v_mul_f32_e32 v233, v233, v115
	v_mul_f32_e32 v213, 0x3f3504f3, v212
	v_mul_f32_e32 v220, 0x3f3504f3, v219
	v_mul_f32_e32 v227, 0x3f3504f3, v226
	v_mul_f32_e32 v234, 0x3f3504f3, v233
	v_fma_f32 v214, |v213|, v187, v188
	v_fma_f32 v221, |v220|, v187, v188
	v_fma_f32 v228, |v227|, v187, v188
	v_fma_f32 v235, |v234|, v187, v188
	v_fma_f32 v214, |v213|, v214, v189
	v_fma_f32 v221, |v220|, v221, v189
	v_fma_f32 v228, |v227|, v228, v189
	v_fma_f32 v235, |v234|, v235, v189
	v_fma_f32 v214, |v213|, v214, v190
	v_fma_f32 v221, |v220|, v221, v190
	v_fma_f32 v228, |v227|, v228, v190
	v_fma_f32 v235, |v234|, v235, v190
	v_fma_f32 v214, |v213|, v214, v191
	v_fma_f32 v221, |v220|, v221, v191
	v_fma_f32 v228, |v227|, v228, v191
	v_fma_f32 v235, |v234|, v235, v191
	v_fma_f32 v214, |v213|, v214, v192
	v_fma_f32 v221, |v220|, v221, v192
	v_fma_f32 v228, |v227|, v228, v192
	v_fma_f32 v235, |v234|, v235, v192
	v_fma_f32 v214, |v213|, v214, v193
	v_fma_f32 v221, |v220|, v221, v193
	v_fma_f32 v228, |v227|, v228, v193
	v_fma_f32 v235, |v234|, v235, v193
	v_fma_f32 v214, |v213|, v214, |v213|
	v_fma_f32 v221, |v220|, v221, |v220|
	v_fma_f32 v228, |v227|, v228, |v227|
	v_fma_f32 v235, |v234|, v235, |v234|
	v_mul_f32_e32 v216, s19, v214
	v_mul_f32_e32 v223, s19, v221
	v_mul_f32_e32 v230, s19, v228
	v_mul_f32_e32 v237, s19, v235
	v_fma_f32 v217, v214, s19, -v216
	v_fma_f32 v224, v221, s19, -v223
	v_fma_f32 v231, v228, s19, -v230
	v_fma_f32 v238, v235, s19, -v237
	v_rndne_f32_e32 v218, v216
	v_rndne_f32_e32 v225, v223
	v_rndne_f32_e32 v232, v230
	v_rndne_f32_e32 v239, v237
	v_fmac_f32_e32 v217, 0xb2a5705f, v214
	v_fmac_f32_e32 v224, 0xb2a5705f, v221
	v_fmac_f32_e32 v231, 0xb2a5705f, v228
	v_fmac_f32_e32 v238, 0xb2a5705f, v235
	v_sub_f32_e32 v216, v216, v218
	v_sub_f32_e32 v223, v223, v225
	v_sub_f32_e32 v230, v230, v232
	v_sub_f32_e32 v237, v237, v239
	v_add_f32_e32 v216, v216, v217
	v_add_f32_e32 v223, v223, v224
	v_add_f32_e32 v230, v230, v231
	v_add_f32_e32 v237, v237, v238
	v_cvt_i32_f32_e32 v218, v218
	v_cvt_i32_f32_e32 v225, v225
	v_cvt_i32_f32_e32 v232, v232
	v_cvt_i32_f32_e32 v239, v239
	v_exp_f32_e32 v216, v216
	v_exp_f32_e32 v223, v223
	v_exp_f32_e32 v230, v230
	v_exp_f32_e32 v237, v237
	v_cmp_nlt_f32_e64 s[4:5], s20, v214
	v_cmp_nlt_f32_e64 s[98:99], s20, v221
	v_cmp_nlt_f32_e64 s[100:101], s20, v228
	v_cmp_nlt_f32_e64 vcc, s20, v235
	v_ldexp_f32 v216, v216, v218
	v_ldexp_f32 v223, v223, v225
	v_ldexp_f32 v230, v230, v232
	v_ldexp_f32 v237, v237, v239
	v_mul_f32_e32 v215, v213, v213
	v_mul_f32_e32 v222, v220, v220
	v_mul_f32_e32 v229, v227, v227
	v_mul_f32_e32 v236, v234, v234
	v_cndmask_b32_e64 v216, 0, v216, s[4:5]
	v_cndmask_b32_e64 v223, 0, v223, s[98:99]
	v_cndmask_b32_e64 v230, 0, v230, s[100:101]
	v_cndmask_b32_e64 v237, 0, v237, vcc
	v_cmp_ngt_f32_e64 s[4:5], s21, v214
	v_cmp_ngt_f32_e64 s[98:99], s21, v221
	v_cmp_ngt_f32_e64 s[100:101], s21, v228
	v_cmp_ngt_f32_e64 vcc, s21, v235
	v_fmamk_f32 v217, v215, 0xba1345e1, v195
	v_fmamk_f32 v224, v222, 0xba1345e1, v195
	v_fmamk_f32 v231, v229, 0xba1345e1, v195
	v_fmamk_f32 v238, v236, 0xba1345e1, v195
	v_fmaak_f32 v217, v215, v217, 0xbcdac9b8
	v_fmaak_f32 v224, v222, v224, 0xbcdac9b8
	v_fmaak_f32 v231, v229, v231, 0xbcdac9b8
	v_fmaak_f32 v238, v236, v238, 0xbcdac9b8
	v_cndmask_b32_e64 v216, v194, v216, s[4:5]
	v_cndmask_b32_e64 v223, v194, v223, s[98:99]
	v_cndmask_b32_e64 v230, v194, v230, s[100:101]
	v_cndmask_b32_e64 v237, v194, v237, vcc
	v_fmaak_f32 v217, v215, v217, 0x3de703be
	v_fmaak_f32 v224, v222, v224, 0x3de703be
	v_fmaak_f32 v231, v229, v231, 0x3de703be
	v_fmaak_f32 v238, v236, v238, 0x3de703be
	v_fmaak_f32 v217, v215, v217, 0xbec09330
	v_fmaak_f32 v224, v222, v224, 0xbec09330
	v_fmaak_f32 v231, v229, v231, 0xbec09330
	v_fmaak_f32 v238, v236, v238, 0xbec09330
	v_sub_f32_e32 v216, 1.0, v216
	v_sub_f32_e32 v223, 1.0, v223
	v_sub_f32_e32 v230, 1.0, v230
	v_sub_f32_e32 v237, 1.0, v237
	v_fmaak_f32 v217, v215, v217, 0x3e0375d0
	v_fmaak_f32 v224, v222, v224, 0x3e0375d0
	v_fmaak_f32 v231, v229, v231, 0x3e0375d0
	v_fmaak_f32 v238, v236, v238, 0x3e0375d0
	v_cmp_nlt_f32_e64 s[4:5], |v213|, 1.0
	v_cmp_nlt_f32_e64 s[98:99], |v220|, 1.0
	v_cmp_nlt_f32_e64 s[100:101], |v227|, 1.0
	v_cmp_nlt_f32_e64 vcc, |v234|, 1.0
	v_fma_f32 v217, |v213|, v217, |v213|
	v_fma_f32 v224, |v220|, v224, |v220|
	v_fma_f32 v231, |v227|, v231, |v227|
	v_fma_f32 v238, |v234|, v238, |v234|
	v_mul_f32_e32 v212, 0.5, v212
	v_mul_f32_e32 v219, 0.5, v219
	v_mul_f32_e32 v226, 0.5, v226
	v_mul_f32_e32 v233, 0.5, v233
	v_mul_f32_e32 v215, v128, v120
	v_mul_f32_e32 v222, v129, v121
	v_mul_f32_e32 v229, v130, v122
	v_mul_f32_e32 v236, v131, v123
	v_cndmask_b32_e64 v216, v217, v216, s[4:5]
	v_cndmask_b32_e64 v223, v224, v223, s[98:99]
	v_cndmask_b32_e64 v230, v231, v230, s[100:101]
	v_cndmask_b32_e64 v237, v238, v237, vcc
	v_bfi_b32 v216, s22, v216, v213
	v_bfi_b32 v223, s22, v223, v220
	v_bfi_b32 v230, s22, v230, v227
	v_bfi_b32 v237, s22, v237, v234
	v_add_f32_e32 v216, 1.0, v216
	v_add_f32_e32 v223, 1.0, v223
	v_add_f32_e32 v230, 1.0, v230
	v_add_f32_e32 v237, 1.0, v237
	v_mul_f32_e32 v212, v212, v216
	v_mul_f32_e32 v219, v219, v223
	v_mul_f32_e32 v226, v226, v230
	v_mul_f32_e32 v233, v233, v237
	v_mul_f32_e32 v212, v128, v212
	v_mul_f32_e32 v219, v129, v219
	v_mul_f32_e32 v226, v130, v226
	v_mul_f32_e32 v233, v131, v233
	v_mul_f32_e32 v240, v120, v212
	v_mul_f32_e32 v241, v121, v219
	v_mul_f32_e32 v242, v122, v226
	v_mul_f32_e32 v243, v123, v233
	global_store_dwordx4 v250, v[240:243], s[94:95]
	v_add_u32_e32 v250, 0x200000, v250
	s_add_u32 s17, s17, 1
	s_cmp_lt_u32 s17, s16
	s_cbranch_scc0 .Lact0_done
	s_waitcnt vmcnt(24)
	v_lshlrev_b32_e32 v196, 2, v96
	v_lshlrev_b32_e32 v197, 2, v97
	v_lshlrev_b32_e32 v198, 2, v98
	v_lshlrev_b32_e32 v199, 2, v99
	ds_read_b32 v112, v196
	ds_read_b32 v113, v197
	ds_read_b32 v114, v198
	ds_read_b32 v115, v199
	global_load_dword v120, v196, s[26:27]
	global_load_dword v121, v197, s[26:27]
	global_load_dword v122, v198, s[26:27]
	global_load_dword v123, v199, s[26:27]
	global_load_dwordx4 v[128:131], v248, s[94:95]
	v_add_u32_e32 v248, 0x200000, v248
	v_min_u32_e32 v248, v248, v249
	global_load_dwordx4 v[104:107], v246, s[94:95]
	v_add_u32_e32 v246, 0x200000, v246
	v_min_u32_e32 v246, v246, v247
	global_load_dwordx4 v[64:67], v244, s[94:95]
	v_add_u32_e32 v251, 0x2040000, v244
	global_load_dwordx4 v[68:71], v251, s[94:95]
	v_add_u32_e32 v251, 0x4080000, v244
	global_load_dwordx4 v[72:75], v251, s[94:95]
	v_add_u32_e32 v251, 0x60c0000, v244
	global_load_dwordx4 v[76:79], v251, s[94:95]
	v_add_u32_e32 v251, 0x8100000, v244
	global_load_dwordx4 v[80:83], v251, s[94:95]
	v_add_u32_e32 v251, 0xa140000, v244
	global_load_dwordx4 v[84:87], v251, s[94:95]
	v_add_u32_e32 v251, 0xc180000, v244
	global_load_dwordx4 v[88:91], v251, s[94:95]
	v_add_u32_e32 v251, 0xe1c0000, v244
	global_load_dwordx4 v[92:95], v251, s[94:95]
	v_add_u32_e32 v244, 0x200000, v244
	v_min_u32_e32 v244, v244, v245
	s_waitcnt vmcnt(24) lgkmcnt(4)
	v_add_f32_e32 v212, 0, v0
	v_add_f32_e32 v219, 0, v1
	v_add_f32_e32 v226, 0, v2
	v_add_f32_e32 v233, 0, v3
	v_add_f32_e32 v212, v212, v4
	v_add_f32_e32 v219, v219, v5
	v_add_f32_e32 v226, v226, v6
	v_add_f32_e32 v233, v233, v7
	v_add_f32_e32 v212, v212, v8
	v_add_f32_e32 v219, v219, v9
	v_add_f32_e32 v226, v226, v10
	v_add_f32_e32 v233, v233, v11
	v_add_f32_e32 v212, v212, v12
	v_add_f32_e32 v219, v219, v13
	v_add_f32_e32 v226, v226, v14
	v_add_f32_e32 v233, v233, v15
	v_add_f32_e32 v212, v212, v16
	v_add_f32_e32 v219, v219, v17
	v_add_f32_e32 v226, v226, v18
	v_add_f32_e32 v233, v233, v19
	v_add_f32_e32 v212, v212, v20
	v_add_f32_e32 v219, v219, v21
	v_add_f32_e32 v226, v226, v22
	v_add_f32_e32 v233, v233, v23
	v_add_f32_e32 v212, v212, v24
	v_add_f32_e32 v219, v219, v25
	v_add_f32_e32 v226, v226, v26
	v_add_f32_e32 v233, v233, v27
	v_add_f32_e32 v212, v212, v28
	v_add_f32_e32 v219, v219, v29
	v_add_f32_e32 v226, v226, v30
	v_add_f32_e32 v233, v233, v31
	v_mul_f32_e32 v212, v212, v116
	v_mul_f32_e32 v219, v219, v117
	v_mul_f32_e32 v226, v226, v118
	v_mul_f32_e32 v233, v233, v119
	v_mul_f32_e32 v213, 0x3f3504f3, v212
	v_mul_f32_e32 v220, 0x3f3504f3, v219
	v_mul_f32_e32 v227, 0x3f3504f3, v226
	v_mul_f32_e32 v234, 0x3f3504f3, v233
	v_fma_f32 v214, |v213|, v187, v188
	v_fma_f32 v221, |v220|, v187, v188
	v_fma_f32 v228, |v227|, v187, v188
	v_fma_f32 v235, |v234|, v187, v188
	v_fma_f32 v214, |v213|, v214, v189
	v_fma_f32 v221, |v220|, v221, v189
	v_fma_f32 v228, |v227|, v228, v189
	v_fma_f32 v235, |v234|, v235, v189
	v_fma_f32 v214, |v213|, v214, v190
	v_fma_f32 v221, |v220|, v221, v190
	v_fma_f32 v228, |v227|, v228, v190
	v_fma_f32 v235, |v234|, v235, v190
	v_fma_f32 v214, |v213|, v214, v191
	v_fma_f32 v221, |v220|, v221, v191
	v_fma_f32 v228, |v227|, v228, v191
	v_fma_f32 v235, |v234|, v235, v191
	v_fma_f32 v214, |v213|, v214, v192
	v_fma_f32 v221, |v220|, v221, v192
	v_fma_f32 v228, |v227|, v228, v192
	v_fma_f32 v235, |v234|, v235, v192
	v_fma_f32 v214, |v213|, v214, v193
	v_fma_f32 v221, |v220|, v221, v193
	v_fma_f32 v228, |v227|, v228, v193
	v_fma_f32 v235, |v234|, v235, v193
	v_fma_f32 v214, |v213|, v214, |v213|
	v_fma_f32 v221, |v220|, v221, |v220|
	v_fma_f32 v228, |v227|, v228, |v227|
	v_fma_f32 v235, |v234|, v235, |v234|
	v_mul_f32_e32 v216, s19, v214
	v_mul_f32_e32 v223, s19, v221
	v_mul_f32_e32 v230, s19, v228
	v_mul_f32_e32 v237, s19, v235
	v_fma_f32 v217, v214, s19, -v216
	v_fma_f32 v224, v221, s19, -v223
	v_fma_f32 v231, v228, s19, -v230
	v_fma_f32 v238, v235, s19, -v237
	v_rndne_f32_e32 v218, v216
	v_rndne_f32_e32 v225, v223
	v_rndne_f32_e32 v232, v230
	v_rndne_f32_e32 v239, v237
	v_fmac_f32_e32 v217, 0xb2a5705f, v214
	v_fmac_f32_e32 v224, 0xb2a5705f, v221
	v_fmac_f32_e32 v231, 0xb2a5705f, v228
	v_fmac_f32_e32 v238, 0xb2a5705f, v235
	v_sub_f32_e32 v216, v216, v218
	v_sub_f32_e32 v223, v223, v225
	v_sub_f32_e32 v230, v230, v232
	v_sub_f32_e32 v237, v237, v239
	v_add_f32_e32 v216, v216, v217
	v_add_f32_e32 v223, v223, v224
	v_add_f32_e32 v230, v230, v231
	v_add_f32_e32 v237, v237, v238
	v_cvt_i32_f32_e32 v218, v218
	v_cvt_i32_f32_e32 v225, v225
	v_cvt_i32_f32_e32 v232, v232
	v_cvt_i32_f32_e32 v239, v239
	v_exp_f32_e32 v216, v216
	v_exp_f32_e32 v223, v223
	v_exp_f32_e32 v230, v230
	v_exp_f32_e32 v237, v237
	v_cmp_nlt_f32_e64 s[4:5], s20, v214
	v_cmp_nlt_f32_e64 s[98:99], s20, v221
	v_cmp_nlt_f32_e64 s[100:101], s20, v228
	v_cmp_nlt_f32_e64 vcc, s20, v235
	v_ldexp_f32 v216, v216, v218
	v_ldexp_f32 v223, v223, v225
	v_ldexp_f32 v230, v230, v232
	v_ldexp_f32 v237, v237, v239
	v_mul_f32_e32 v215, v213, v213
	v_mul_f32_e32 v222, v220, v220
	v_mul_f32_e32 v229, v227, v227
	v_mul_f32_e32 v236, v234, v234
	v_cndmask_b32_e64 v216, 0, v216, s[4:5]
	v_cndmask_b32_e64 v223, 0, v223, s[98:99]
	v_cndmask_b32_e64 v230, 0, v230, s[100:101]
	v_cndmask_b32_e64 v237, 0, v237, vcc
	v_cmp_ngt_f32_e64 s[4:5], s21, v214
	v_cmp_ngt_f32_e64 s[98:99], s21, v221
	v_cmp_ngt_f32_e64 s[100:101], s21, v228
	v_cmp_ngt_f32_e64 vcc, s21, v235
	v_fmamk_f32 v217, v215, 0xba1345e1, v195
	v_fmamk_f32 v224, v222, 0xba1345e1, v195
	v_fmamk_f32 v231, v229, 0xba1345e1, v195
	v_fmamk_f32 v238, v236, 0xba1345e1, v195
	v_fmaak_f32 v217, v215, v217, 0xbcdac9b8
	v_fmaak_f32 v224, v222, v224, 0xbcdac9b8
	v_fmaak_f32 v231, v229, v231, 0xbcdac9b8
	v_fmaak_f32 v238, v236, v238, 0xbcdac9b8
	v_cndmask_b32_e64 v216, v194, v216, s[4:5]
	v_cndmask_b32_e64 v223, v194, v223, s[98:99]
	v_cndmask_b32_e64 v230, v194, v230, s[100:101]
	v_cndmask_b32_e64 v237, v194, v237, vcc
	v_fmaak_f32 v217, v215, v217, 0x3de703be
	v_fmaak_f32 v224, v222, v224, 0x3de703be
	v_fmaak_f32 v231, v229, v231, 0x3de703be
	v_fmaak_f32 v238, v236, v238, 0x3de703be
	v_fmaak_f32 v217, v215, v217, 0xbec09330
	v_fmaak_f32 v224, v222, v224, 0xbec09330
	v_fmaak_f32 v231, v229, v231, 0xbec09330
	v_fmaak_f32 v238, v236, v238, 0xbec09330
	v_sub_f32_e32 v216, 1.0, v216
	v_sub_f32_e32 v223, 1.0, v223
	v_sub_f32_e32 v230, 1.0, v230
	v_sub_f32_e32 v237, 1.0, v237
	v_fmaak_f32 v217, v215, v217, 0x3e0375d0
	v_fmaak_f32 v224, v222, v224, 0x3e0375d0
	v_fmaak_f32 v231, v229, v231, 0x3e0375d0
	v_fmaak_f32 v238, v236, v238, 0x3e0375d0
	v_cmp_nlt_f32_e64 s[4:5], |v213|, 1.0
	v_cmp_nlt_f32_e64 s[98:99], |v220|, 1.0
	v_cmp_nlt_f32_e64 s[100:101], |v227|, 1.0
	v_cmp_nlt_f32_e64 vcc, |v234|, 1.0
	v_fma_f32 v217, |v213|, v217, |v213|
	v_fma_f32 v224, |v220|, v224, |v220|
	v_fma_f32 v231, |v227|, v231, |v227|
	v_fma_f32 v238, |v234|, v238, |v234|
	v_mul_f32_e32 v212, 0.5, v212
	v_mul_f32_e32 v219, 0.5, v219
	v_mul_f32_e32 v226, 0.5, v226
	v_mul_f32_e32 v233, 0.5, v233
	v_mul_f32_e32 v215, v132, v124
	v_mul_f32_e32 v222, v133, v125
	v_mul_f32_e32 v229, v134, v126
	v_mul_f32_e32 v236, v135, v127
	v_cndmask_b32_e64 v216, v217, v216, s[4:5]
	v_cndmask_b32_e64 v223, v224, v223, s[98:99]
	v_cndmask_b32_e64 v230, v231, v230, s[100:101]
	v_cndmask_b32_e64 v237, v238, v237, vcc
	v_bfi_b32 v216, s22, v216, v213
	v_bfi_b32 v223, s22, v223, v220
	v_bfi_b32 v230, s22, v230, v227
	v_bfi_b32 v237, s22, v237, v234
	v_add_f32_e32 v216, 1.0, v216
	v_add_f32_e32 v223, 1.0, v223
	v_add_f32_e32 v230, 1.0, v230
	v_add_f32_e32 v237, 1.0, v237
	v_mul_f32_e32 v212, v212, v216
	v_mul_f32_e32 v219, v219, v223
	v_mul_f32_e32 v226, v226, v230
	v_mul_f32_e32 v233, v233, v237
	v_mul_f32_e32 v212, v132, v212
	v_mul_f32_e32 v219, v133, v219
	v_mul_f32_e32 v226, v134, v226
	v_mul_f32_e32 v233, v135, v233
	v_mul_f32_e32 v240, v124, v212
	v_mul_f32_e32 v241, v125, v219
	v_mul_f32_e32 v242, v126, v226
	v_mul_f32_e32 v243, v127, v233
	global_store_dwordx4 v250, v[240:243], s[94:95]
	v_add_u32_e32 v250, 0x200000, v250
	s_add_u32 s17, s17, 1
	s_cmp_lt_u32 s17, s16
	s_cbranch_scc0 .Lact0_done
	s_waitcnt vmcnt(24)
	v_lshlrev_b32_e32 v196, 2, v100
	v_lshlrev_b32_e32 v197, 2, v101
	v_lshlrev_b32_e32 v198, 2, v102
	v_lshlrev_b32_e32 v199, 2, v103
	ds_read_b32 v116, v196
	ds_read_b32 v117, v197
	ds_read_b32 v118, v198
	ds_read_b32 v119, v199
	global_load_dword v124, v196, s[26:27]
	global_load_dword v125, v197, s[26:27]
	global_load_dword v126, v198, s[26:27]
	global_load_dword v127, v199, s[26:27]
	global_load_dwordx4 v[132:135], v248, s[94:95]
	v_add_u32_e32 v248, 0x200000, v248
	v_min_u32_e32 v248, v248, v249
	global_load_dwordx4 v[108:111], v246, s[94:95]
	v_add_u32_e32 v246, 0x200000, v246
	v_min_u32_e32 v246, v246, v247
	global_load_dwordx4 v[0:3], v244, s[94:95]
	v_add_u32_e32 v251, 0x2040000, v244
	global_load_dwordx4 v[4:7], v251, s[94:95]
	v_add_u32_e32 v251, 0x4080000, v244
	global_load_dwordx4 v[8:11], v251, s[94:95]
	v_add_u32_e32 v251, 0x60c0000, v244
	global_load_dwordx4 v[12:15], v251, s[94:95]
	v_add_u32_e32 v251, 0x8100000, v244
	global_load_dwordx4 v[16:19], v251, s[94:95]
	v_add_u32_e32 v251, 0xa140000, v244
	global_load_dwordx4 v[20:23], v251, s[94:95]
	v_add_u32_e32 v251, 0xc180000, v244
	global_load_dwordx4 v[24:27], v251, s[94:95]
	v_add_u32_e32 v251, 0xe1c0000, v244
	global_load_dwordx4 v[28:31], v251, s[94:95]
	v_add_u32_e32 v244, 0x200000, v244
	v_min_u32_e32 v244, v244, v245
	s_waitcnt vmcnt(24) lgkmcnt(4)
	v_add_f32_e32 v212, 0, v32
	v_add_f32_e32 v219, 0, v33
	v_add_f32_e32 v226, 0, v34
	v_add_f32_e32 v233, 0, v35
	v_add_f32_e32 v212, v212, v36
	v_add_f32_e32 v219, v219, v37
	v_add_f32_e32 v226, v226, v38
	v_add_f32_e32 v233, v233, v39
	v_add_f32_e32 v212, v212, v40
	v_add_f32_e32 v219, v219, v41
	v_add_f32_e32 v226, v226, v42
	v_add_f32_e32 v233, v233, v43
	v_add_f32_e32 v212, v212, v44
	v_add_f32_e32 v219, v219, v45
	v_add_f32_e32 v226, v226, v46
	v_add_f32_e32 v233, v233, v47
	v_add_f32_e32 v212, v212, v48
	v_add_f32_e32 v219, v219, v49
	v_add_f32_e32 v226, v226, v50
	v_add_f32_e32 v233, v233, v51
	v_add_f32_e32 v212, v212, v52
	v_add_f32_e32 v219, v219, v53
	v_add_f32_e32 v226, v226, v54
	v_add_f32_e32 v233, v233, v55
	v_add_f32_e32 v212, v212, v56
	v_add_f32_e32 v219, v219, v57
	v_add_f32_e32 v226, v226, v58
	v_add_f32_e32 v233, v233, v59
	v_add_f32_e32 v212, v212, v60
	v_add_f32_e32 v219, v219, v61
	v_add_f32_e32 v226, v226, v62
	v_add_f32_e32 v233, v233, v63
	v_mul_f32_e32 v212, v212, v112
	v_mul_f32_e32 v219, v219, v113
	v_mul_f32_e32 v226, v226, v114
	v_mul_f32_e32 v233, v233, v115
	v_mul_f32_e32 v213, 0x3f3504f3, v212
	v_mul_f32_e32 v220, 0x3f3504f3, v219
	v_mul_f32_e32 v227, 0x3f3504f3, v226
	v_mul_f32_e32 v234, 0x3f3504f3, v233
	v_fma_f32 v214, |v213|, v187, v188
	v_fma_f32 v221, |v220|, v187, v188
	v_fma_f32 v228, |v227|, v187, v188
	v_fma_f32 v235, |v234|, v187, v188
	v_fma_f32 v214, |v213|, v214, v189
	v_fma_f32 v221, |v220|, v221, v189
	v_fma_f32 v228, |v227|, v228, v189
	v_fma_f32 v235, |v234|, v235, v189
	v_fma_f32 v214, |v213|, v214, v190
	v_fma_f32 v221, |v220|, v221, v190
	v_fma_f32 v228, |v227|, v228, v190
	v_fma_f32 v235, |v234|, v235, v190
	v_fma_f32 v214, |v213|, v214, v191
	v_fma_f32 v221, |v220|, v221, v191
	v_fma_f32 v228, |v227|, v228, v191
	v_fma_f32 v235, |v234|, v235, v191
	v_fma_f32 v214, |v213|, v214, v192
	v_fma_f32 v221, |v220|, v221, v192
	v_fma_f32 v228, |v227|, v228, v192
	v_fma_f32 v235, |v234|, v235, v192
	v_fma_f32 v214, |v213|, v214, v193
	v_fma_f32 v221, |v220|, v221, v193
	v_fma_f32 v228, |v227|, v228, v193
	v_fma_f32 v235, |v234|, v235, v193
	v_fma_f32 v214, |v213|, v214, |v213|
	v_fma_f32 v221, |v220|, v221, |v220|
	v_fma_f32 v228, |v227|, v228, |v227|
	v_fma_f32 v235, |v234|, v235, |v234|
	v_mul_f32_e32 v216, s19, v214
	v_mul_f32_e32 v223, s19, v221
	v_mul_f32_e32 v230, s19, v228
	v_mul_f32_e32 v237, s19, v235
	v_fma_f32 v217, v214, s19, -v216
	v_fma_f32 v224, v221, s19, -v223
	v_fma_f32 v231, v228, s19, -v230
	v_fma_f32 v238, v235, s19, -v237
	v_rndne_f32_e32 v218, v216
	v_rndne_f32_e32 v225, v223
	v_rndne_f32_e32 v232, v230
	v_rndne_f32_e32 v239, v237
	v_fmac_f32_e32 v217, 0xb2a5705f, v214
	v_fmac_f32_e32 v224, 0xb2a5705f, v221
	v_fmac_f32_e32 v231, 0xb2a5705f, v228
	v_fmac_f32_e32 v238, 0xb2a5705f, v235
	v_sub_f32_e32 v216, v216, v218
	v_sub_f32_e32 v223, v223, v225
	v_sub_f32_e32 v230, v230, v232
	v_sub_f32_e32 v237, v237, v239
	v_add_f32_e32 v216, v216, v217
	v_add_f32_e32 v223, v223, v224
	v_add_f32_e32 v230, v230, v231
	v_add_f32_e32 v237, v237, v238
	v_cvt_i32_f32_e32 v218, v218
	v_cvt_i32_f32_e32 v225, v225
	v_cvt_i32_f32_e32 v232, v232
	v_cvt_i32_f32_e32 v239, v239
	v_exp_f32_e32 v216, v216
	v_exp_f32_e32 v223, v223
	v_exp_f32_e32 v230, v230
	v_exp_f32_e32 v237, v237
	v_cmp_nlt_f32_e64 s[4:5], s20, v214
	v_cmp_nlt_f32_e64 s[98:99], s20, v221
	v_cmp_nlt_f32_e64 s[100:101], s20, v228
	v_cmp_nlt_f32_e64 vcc, s20, v235
	v_ldexp_f32 v216, v216, v218
	v_ldexp_f32 v223, v223, v225
	v_ldexp_f32 v230, v230, v232
	v_ldexp_f32 v237, v237, v239
	v_mul_f32_e32 v215, v213, v213
	v_mul_f32_e32 v222, v220, v220
	v_mul_f32_e32 v229, v227, v227
	v_mul_f32_e32 v236, v234, v234
	v_cndmask_b32_e64 v216, 0, v216, s[4:5]
	v_cndmask_b32_e64 v223, 0, v223, s[98:99]
	v_cndmask_b32_e64 v230, 0, v230, s[100:101]
	v_cndmask_b32_e64 v237, 0, v237, vcc
	v_cmp_ngt_f32_e64 s[4:5], s21, v214
	v_cmp_ngt_f32_e64 s[98:99], s21, v221
	v_cmp_ngt_f32_e64 s[100:101], s21, v228
	v_cmp_ngt_f32_e64 vcc, s21, v235
	v_fmamk_f32 v217, v215, 0xba1345e1, v195
	v_fmamk_f32 v224, v222, 0xba1345e1, v195
	v_fmamk_f32 v231, v229, 0xba1345e1, v195
	v_fmamk_f32 v238, v236, 0xba1345e1, v195
	v_fmaak_f32 v217, v215, v217, 0xbcdac9b8
	v_fmaak_f32 v224, v222, v224, 0xbcdac9b8
	v_fmaak_f32 v231, v229, v231, 0xbcdac9b8
	v_fmaak_f32 v238, v236, v238, 0xbcdac9b8
	v_cndmask_b32_e64 v216, v194, v216, s[4:5]
	v_cndmask_b32_e64 v223, v194, v223, s[98:99]
	v_cndmask_b32_e64 v230, v194, v230, s[100:101]
	v_cndmask_b32_e64 v237, v194, v237, vcc
	v_fmaak_f32 v217, v215, v217, 0x3de703be
	v_fmaak_f32 v224, v222, v224, 0x3de703be
	v_fmaak_f32 v231, v229, v231, 0x3de703be
	v_fmaak_f32 v238, v236, v238, 0x3de703be
	v_fmaak_f32 v217, v215, v217, 0xbec09330
	v_fmaak_f32 v224, v222, v224, 0xbec09330
	v_fmaak_f32 v231, v229, v231, 0xbec09330
	v_fmaak_f32 v238, v236, v238, 0xbec09330
	v_sub_f32_e32 v216, 1.0, v216
	v_sub_f32_e32 v223, 1.0, v223
	v_sub_f32_e32 v230, 1.0, v230
	v_sub_f32_e32 v237, 1.0, v237
	v_fmaak_f32 v217, v215, v217, 0x3e0375d0
	v_fmaak_f32 v224, v222, v224, 0x3e0375d0
	v_fmaak_f32 v231, v229, v231, 0x3e0375d0
	v_fmaak_f32 v238, v236, v238, 0x3e0375d0
	v_cmp_nlt_f32_e64 s[4:5], |v213|, 1.0
	v_cmp_nlt_f32_e64 s[98:99], |v220|, 1.0
	v_cmp_nlt_f32_e64 s[100:101], |v227|, 1.0
	v_cmp_nlt_f32_e64 vcc, |v234|, 1.0
	v_fma_f32 v217, |v213|, v217, |v213|
	v_fma_f32 v224, |v220|, v224, |v220|
	v_fma_f32 v231, |v227|, v231, |v227|
	v_fma_f32 v238, |v234|, v238, |v234|
	v_mul_f32_e32 v212, 0.5, v212
	v_mul_f32_e32 v219, 0.5, v219
	v_mul_f32_e32 v226, 0.5, v226
	v_mul_f32_e32 v233, 0.5, v233
	v_mul_f32_e32 v215, v128, v120
	v_mul_f32_e32 v222, v129, v121
	v_mul_f32_e32 v229, v130, v122
	v_mul_f32_e32 v236, v131, v123
	v_cndmask_b32_e64 v216, v217, v216, s[4:5]
	v_cndmask_b32_e64 v223, v224, v223, s[98:99]
	v_cndmask_b32_e64 v230, v231, v230, s[100:101]
	v_cndmask_b32_e64 v237, v238, v237, vcc
	v_bfi_b32 v216, s22, v216, v213
	v_bfi_b32 v223, s22, v223, v220
	v_bfi_b32 v230, s22, v230, v227
	v_bfi_b32 v237, s22, v237, v234
	v_add_f32_e32 v216, 1.0, v216
	v_add_f32_e32 v223, 1.0, v223
	v_add_f32_e32 v230, 1.0, v230
	v_add_f32_e32 v237, 1.0, v237
	v_mul_f32_e32 v212, v212, v216
	v_mul_f32_e32 v219, v219, v223
	v_mul_f32_e32 v226, v226, v230
	v_mul_f32_e32 v233, v233, v237
	v_mul_f32_e32 v212, v128, v212
	v_mul_f32_e32 v219, v129, v219
	v_mul_f32_e32 v226, v130, v226
	v_mul_f32_e32 v233, v131, v233
	v_mul_f32_e32 v240, v120, v212
	v_mul_f32_e32 v241, v121, v219
	v_mul_f32_e32 v242, v122, v226
	v_mul_f32_e32 v243, v123, v233
	global_store_dwordx4 v250, v[240:243], s[94:95]
	v_add_u32_e32 v250, 0x200000, v250
	s_add_u32 s17, s17, 1
	s_cmp_lt_u32 s17, s16
	s_cbranch_scc0 .Lact0_done
	s_waitcnt vmcnt(24)
	v_lshlrev_b32_e32 v196, 2, v104
	v_lshlrev_b32_e32 v197, 2, v105
	v_lshlrev_b32_e32 v198, 2, v106
	v_lshlrev_b32_e32 v199, 2, v107
	ds_read_b32 v112, v196
	ds_read_b32 v113, v197
	ds_read_b32 v114, v198
	ds_read_b32 v115, v199
	global_load_dword v120, v196, s[26:27]
	global_load_dword v121, v197, s[26:27]
	global_load_dword v122, v198, s[26:27]
	global_load_dword v123, v199, s[26:27]
	global_load_dwordx4 v[128:131], v248, s[94:95]
	v_add_u32_e32 v248, 0x200000, v248
	v_min_u32_e32 v248, v248, v249
	global_load_dwordx4 v[96:99], v246, s[94:95]
	v_add_u32_e32 v246, 0x200000, v246
	v_min_u32_e32 v246, v246, v247
	global_load_dwordx4 v[32:35], v244, s[94:95]
	v_add_u32_e32 v251, 0x2040000, v244
	global_load_dwordx4 v[36:39], v251, s[94:95]
	v_add_u32_e32 v251, 0x4080000, v244
	global_load_dwordx4 v[40:43], v251, s[94:95]
	v_add_u32_e32 v251, 0x60c0000, v244
	global_load_dwordx4 v[44:47], v251, s[94:95]
	v_add_u32_e32 v251, 0x8100000, v244
	global_load_dwordx4 v[48:51], v251, s[94:95]
	v_add_u32_e32 v251, 0xa140000, v244
	global_load_dwordx4 v[52:55], v251, s[94:95]
	v_add_u32_e32 v251, 0xc180000, v244
	global_load_dwordx4 v[56:59], v251, s[94:95]
	v_add_u32_e32 v251, 0xe1c0000, v244
	global_load_dwordx4 v[60:63], v251, s[94:95]
	v_add_u32_e32 v244, 0x200000, v244
	v_min_u32_e32 v244, v244, v245
	s_waitcnt vmcnt(24) lgkmcnt(4)
	v_add_f32_e32 v212, 0, v64
	v_add_f32_e32 v219, 0, v65
	v_add_f32_e32 v226, 0, v66
	v_add_f32_e32 v233, 0, v67
	v_add_f32_e32 v212, v212, v68
	v_add_f32_e32 v219, v219, v69
	v_add_f32_e32 v226, v226, v70
	v_add_f32_e32 v233, v233, v71
	v_add_f32_e32 v212, v212, v72
	v_add_f32_e32 v219, v219, v73
	v_add_f32_e32 v226, v226, v74
	v_add_f32_e32 v233, v233, v75
	v_add_f32_e32 v212, v212, v76
	v_add_f32_e32 v219, v219, v77
	v_add_f32_e32 v226, v226, v78
	v_add_f32_e32 v233, v233, v79
	v_add_f32_e32 v212, v212, v80
	v_add_f32_e32 v219, v219, v81
	v_add_f32_e32 v226, v226, v82
	v_add_f32_e32 v233, v233, v83
	v_add_f32_e32 v212, v212, v84
	v_add_f32_e32 v219, v219, v85
	v_add_f32_e32 v226, v226, v86
	v_add_f32_e32 v233, v233, v87
	v_add_f32_e32 v212, v212, v88
	v_add_f32_e32 v219, v219, v89
	v_add_f32_e32 v226, v226, v90
	v_add_f32_e32 v233, v233, v91
	v_add_f32_e32 v212, v212, v92
	v_add_f32_e32 v219, v219, v93
	v_add_f32_e32 v226, v226, v94
	v_add_f32_e32 v233, v233, v95
	v_mul_f32_e32 v212, v212, v116
	v_mul_f32_e32 v219, v219, v117
	v_mul_f32_e32 v226, v226, v118
	v_mul_f32_e32 v233, v233, v119
	v_mul_f32_e32 v213, 0x3f3504f3, v212
	v_mul_f32_e32 v220, 0x3f3504f3, v219
	v_mul_f32_e32 v227, 0x3f3504f3, v226
	v_mul_f32_e32 v234, 0x3f3504f3, v233
	v_fma_f32 v214, |v213|, v187, v188
	v_fma_f32 v221, |v220|, v187, v188
	v_fma_f32 v228, |v227|, v187, v188
	v_fma_f32 v235, |v234|, v187, v188
	v_fma_f32 v214, |v213|, v214, v189
	v_fma_f32 v221, |v220|, v221, v189
	v_fma_f32 v228, |v227|, v228, v189
	v_fma_f32 v235, |v234|, v235, v189
	v_fma_f32 v214, |v213|, v214, v190
	v_fma_f32 v221, |v220|, v221, v190
	v_fma_f32 v228, |v227|, v228, v190
	v_fma_f32 v235, |v234|, v235, v190
	v_fma_f32 v214, |v213|, v214, v191
	v_fma_f32 v221, |v220|, v221, v191
	v_fma_f32 v228, |v227|, v228, v191
	v_fma_f32 v235, |v234|, v235, v191
	v_fma_f32 v214, |v213|, v214, v192
	v_fma_f32 v221, |v220|, v221, v192
	v_fma_f32 v228, |v227|, v228, v192
	v_fma_f32 v235, |v234|, v235, v192
	v_fma_f32 v214, |v213|, v214, v193
	v_fma_f32 v221, |v220|, v221, v193
	v_fma_f32 v228, |v227|, v228, v193
	v_fma_f32 v235, |v234|, v235, v193
	v_fma_f32 v214, |v213|, v214, |v213|
	v_fma_f32 v221, |v220|, v221, |v220|
	v_fma_f32 v228, |v227|, v228, |v227|
	v_fma_f32 v235, |v234|, v235, |v234|
	v_mul_f32_e32 v216, s19, v214
	v_mul_f32_e32 v223, s19, v221
	v_mul_f32_e32 v230, s19, v228
	v_mul_f32_e32 v237, s19, v235
	v_fma_f32 v217, v214, s19, -v216
	v_fma_f32 v224, v221, s19, -v223
	v_fma_f32 v231, v228, s19, -v230
	v_fma_f32 v238, v235, s19, -v237
	v_rndne_f32_e32 v218, v216
	v_rndne_f32_e32 v225, v223
	v_rndne_f32_e32 v232, v230
	v_rndne_f32_e32 v239, v237
	v_fmac_f32_e32 v217, 0xb2a5705f, v214
	v_fmac_f32_e32 v224, 0xb2a5705f, v221
	v_fmac_f32_e32 v231, 0xb2a5705f, v228
	v_fmac_f32_e32 v238, 0xb2a5705f, v235
	v_sub_f32_e32 v216, v216, v218
	v_sub_f32_e32 v223, v223, v225
	v_sub_f32_e32 v230, v230, v232
	v_sub_f32_e32 v237, v237, v239
	v_add_f32_e32 v216, v216, v217
	v_add_f32_e32 v223, v223, v224
	v_add_f32_e32 v230, v230, v231
	v_add_f32_e32 v237, v237, v238
	v_cvt_i32_f32_e32 v218, v218
	v_cvt_i32_f32_e32 v225, v225
	v_cvt_i32_f32_e32 v232, v232
	v_cvt_i32_f32_e32 v239, v239
	v_exp_f32_e32 v216, v216
	v_exp_f32_e32 v223, v223
	v_exp_f32_e32 v230, v230
	v_exp_f32_e32 v237, v237
	v_cmp_nlt_f32_e64 s[4:5], s20, v214
	v_cmp_nlt_f32_e64 s[98:99], s20, v221
	v_cmp_nlt_f32_e64 s[100:101], s20, v228
	v_cmp_nlt_f32_e64 vcc, s20, v235
	v_ldexp_f32 v216, v216, v218
	v_ldexp_f32 v223, v223, v225
	v_ldexp_f32 v230, v230, v232
	v_ldexp_f32 v237, v237, v239
	v_mul_f32_e32 v215, v213, v213
	v_mul_f32_e32 v222, v220, v220
	v_mul_f32_e32 v229, v227, v227
	v_mul_f32_e32 v236, v234, v234
	v_cndmask_b32_e64 v216, 0, v216, s[4:5]
	v_cndmask_b32_e64 v223, 0, v223, s[98:99]
	v_cndmask_b32_e64 v230, 0, v230, s[100:101]
	v_cndmask_b32_e64 v237, 0, v237, vcc
	v_cmp_ngt_f32_e64 s[4:5], s21, v214
	v_cmp_ngt_f32_e64 s[98:99], s21, v221
	v_cmp_ngt_f32_e64 s[100:101], s21, v228
	v_cmp_ngt_f32_e64 vcc, s21, v235
	v_fmamk_f32 v217, v215, 0xba1345e1, v195
	v_fmamk_f32 v224, v222, 0xba1345e1, v195
	v_fmamk_f32 v231, v229, 0xba1345e1, v195
	v_fmamk_f32 v238, v236, 0xba1345e1, v195
	v_fmaak_f32 v217, v215, v217, 0xbcdac9b8
	v_fmaak_f32 v224, v222, v224, 0xbcdac9b8
	v_fmaak_f32 v231, v229, v231, 0xbcdac9b8
	v_fmaak_f32 v238, v236, v238, 0xbcdac9b8
	v_cndmask_b32_e64 v216, v194, v216, s[4:5]
	v_cndmask_b32_e64 v223, v194, v223, s[98:99]
	v_cndmask_b32_e64 v230, v194, v230, s[100:101]
	v_cndmask_b32_e64 v237, v194, v237, vcc
	v_fmaak_f32 v217, v215, v217, 0x3de703be
	v_fmaak_f32 v224, v222, v224, 0x3de703be
	v_fmaak_f32 v231, v229, v231, 0x3de703be
	v_fmaak_f32 v238, v236, v238, 0x3de703be
	v_fmaak_f32 v217, v215, v217, 0xbec09330
	v_fmaak_f32 v224, v222, v224, 0xbec09330
	v_fmaak_f32 v231, v229, v231, 0xbec09330
	v_fmaak_f32 v238, v236, v238, 0xbec09330
	v_sub_f32_e32 v216, 1.0, v216
	v_sub_f32_e32 v223, 1.0, v223
	v_sub_f32_e32 v230, 1.0, v230
	v_sub_f32_e32 v237, 1.0, v237
	v_fmaak_f32 v217, v215, v217, 0x3e0375d0
	v_fmaak_f32 v224, v222, v224, 0x3e0375d0
	v_fmaak_f32 v231, v229, v231, 0x3e0375d0
	v_fmaak_f32 v238, v236, v238, 0x3e0375d0
	v_cmp_nlt_f32_e64 s[4:5], |v213|, 1.0
	v_cmp_nlt_f32_e64 s[98:99], |v220|, 1.0
	v_cmp_nlt_f32_e64 s[100:101], |v227|, 1.0
	v_cmp_nlt_f32_e64 vcc, |v234|, 1.0
	v_fma_f32 v217, |v213|, v217, |v213|
	v_fma_f32 v224, |v220|, v224, |v220|
	v_fma_f32 v231, |v227|, v231, |v227|
	v_fma_f32 v238, |v234|, v238, |v234|
	v_mul_f32_e32 v212, 0.5, v212
	v_mul_f32_e32 v219, 0.5, v219
	v_mul_f32_e32 v226, 0.5, v226
	v_mul_f32_e32 v233, 0.5, v233
	v_mul_f32_e32 v215, v132, v124
	v_mul_f32_e32 v222, v133, v125
	v_mul_f32_e32 v229, v134, v126
	v_mul_f32_e32 v236, v135, v127
	v_cndmask_b32_e64 v216, v217, v216, s[4:5]
	v_cndmask_b32_e64 v223, v224, v223, s[98:99]
	v_cndmask_b32_e64 v230, v231, v230, s[100:101]
	v_cndmask_b32_e64 v237, v238, v237, vcc
	v_bfi_b32 v216, s22, v216, v213
	v_bfi_b32 v223, s22, v223, v220
	v_bfi_b32 v230, s22, v230, v227
	v_bfi_b32 v237, s22, v237, v234
	v_add_f32_e32 v216, 1.0, v216
	v_add_f32_e32 v223, 1.0, v223
	v_add_f32_e32 v230, 1.0, v230
	v_add_f32_e32 v237, 1.0, v237
	v_mul_f32_e32 v212, v212, v216
	v_mul_f32_e32 v219, v219, v223
	v_mul_f32_e32 v226, v226, v230
	v_mul_f32_e32 v233, v233, v237
	v_mul_f32_e32 v212, v132, v212
	v_mul_f32_e32 v219, v133, v219
	v_mul_f32_e32 v226, v134, v226
	v_mul_f32_e32 v233, v135, v233
	v_mul_f32_e32 v240, v124, v212
	v_mul_f32_e32 v241, v125, v219
	v_mul_f32_e32 v242, v126, v226
	v_mul_f32_e32 v243, v127, v233
	global_store_dwordx4 v250, v[240:243], s[94:95]
	v_add_u32_e32 v250, 0x200000, v250
	s_add_u32 s17, s17, 1
	s_cmp_lt_u32 s17, s16
	s_cbranch_scc0 .Lact0_done
	s_waitcnt vmcnt(24)
	v_lshlrev_b32_e32 v196, 2, v108
	v_lshlrev_b32_e32 v197, 2, v109
	v_lshlrev_b32_e32 v198, 2, v110
	v_lshlrev_b32_e32 v199, 2, v111
	ds_read_b32 v116, v196
	ds_read_b32 v117, v197
	ds_read_b32 v118, v198
	ds_read_b32 v119, v199
	global_load_dword v124, v196, s[26:27]
	global_load_dword v125, v197, s[26:27]
	global_load_dword v126, v198, s[26:27]
	global_load_dword v127, v199, s[26:27]
	global_load_dwordx4 v[132:135], v248, s[94:95]
	v_add_u32_e32 v248, 0x200000, v248
	v_min_u32_e32 v248, v248, v249
	global_load_dwordx4 v[100:103], v246, s[94:95]
	v_add_u32_e32 v246, 0x200000, v246
	v_min_u32_e32 v246, v246, v247
	global_load_dwordx4 v[64:67], v244, s[94:95]
	v_add_u32_e32 v251, 0x2040000, v244
	global_load_dwordx4 v[68:71], v251, s[94:95]
	v_add_u32_e32 v251, 0x4080000, v244
	global_load_dwordx4 v[72:75], v251, s[94:95]
	v_add_u32_e32 v251, 0x60c0000, v244
	global_load_dwordx4 v[76:79], v251, s[94:95]
	v_add_u32_e32 v251, 0x8100000, v244
	global_load_dwordx4 v[80:83], v251, s[94:95]
	v_add_u32_e32 v251, 0xa140000, v244
	global_load_dwordx4 v[84:87], v251, s[94:95]
	v_add_u32_e32 v251, 0xc180000, v244
	global_load_dwordx4 v[88:91], v251, s[94:95]
	v_add_u32_e32 v251, 0xe1c0000, v244
	global_load_dwordx4 v[92:95], v251, s[94:95]
	v_add_u32_e32 v244, 0x200000, v244
	v_min_u32_e32 v244, v244, v245
	s_waitcnt vmcnt(24) lgkmcnt(4)
	v_add_f32_e32 v212, 0, v0
	v_add_f32_e32 v219, 0, v1
	v_add_f32_e32 v226, 0, v2
	v_add_f32_e32 v233, 0, v3
	v_add_f32_e32 v212, v212, v4
	v_add_f32_e32 v219, v219, v5
	v_add_f32_e32 v226, v226, v6
	v_add_f32_e32 v233, v233, v7
	v_add_f32_e32 v212, v212, v8
	v_add_f32_e32 v219, v219, v9
	v_add_f32_e32 v226, v226, v10
	v_add_f32_e32 v233, v233, v11
	v_add_f32_e32 v212, v212, v12
	v_add_f32_e32 v219, v219, v13
	v_add_f32_e32 v226, v226, v14
	v_add_f32_e32 v233, v233, v15
	v_add_f32_e32 v212, v212, v16
	v_add_f32_e32 v219, v219, v17
	v_add_f32_e32 v226, v226, v18
	v_add_f32_e32 v233, v233, v19
	v_add_f32_e32 v212, v212, v20
	v_add_f32_e32 v219, v219, v21
	v_add_f32_e32 v226, v226, v22
	v_add_f32_e32 v233, v233, v23
	v_add_f32_e32 v212, v212, v24
	v_add_f32_e32 v219, v219, v25
	v_add_f32_e32 v226, v226, v26
	v_add_f32_e32 v233, v233, v27
	v_add_f32_e32 v212, v212, v28
	v_add_f32_e32 v219, v219, v29
	v_add_f32_e32 v226, v226, v30
	v_add_f32_e32 v233, v233, v31
	v_mul_f32_e32 v212, v212, v112
	v_mul_f32_e32 v219, v219, v113
	v_mul_f32_e32 v226, v226, v114
	v_mul_f32_e32 v233, v233, v115
	v_mul_f32_e32 v213, 0x3f3504f3, v212
	v_mul_f32_e32 v220, 0x3f3504f3, v219
	v_mul_f32_e32 v227, 0x3f3504f3, v226
	v_mul_f32_e32 v234, 0x3f3504f3, v233
	v_fma_f32 v214, |v213|, v187, v188
	v_fma_f32 v221, |v220|, v187, v188
	v_fma_f32 v228, |v227|, v187, v188
	v_fma_f32 v235, |v234|, v187, v188
	v_fma_f32 v214, |v213|, v214, v189
	v_fma_f32 v221, |v220|, v221, v189
	v_fma_f32 v228, |v227|, v228, v189
	v_fma_f32 v235, |v234|, v235, v189
	v_fma_f32 v214, |v213|, v214, v190
	v_fma_f32 v221, |v220|, v221, v190
	v_fma_f32 v228, |v227|, v228, v190
	v_fma_f32 v235, |v234|, v235, v190
	v_fma_f32 v214, |v213|, v214, v191
	v_fma_f32 v221, |v220|, v221, v191
	v_fma_f32 v228, |v227|, v228, v191
	v_fma_f32 v235, |v234|, v235, v191
	v_fma_f32 v214, |v213|, v214, v192
	v_fma_f32 v221, |v220|, v221, v192
	v_fma_f32 v228, |v227|, v228, v192
	v_fma_f32 v235, |v234|, v235, v192
	v_fma_f32 v214, |v213|, v214, v193
	v_fma_f32 v221, |v220|, v221, v193
	v_fma_f32 v228, |v227|, v228, v193
	v_fma_f32 v235, |v234|, v235, v193
	v_fma_f32 v214, |v213|, v214, |v213|
	v_fma_f32 v221, |v220|, v221, |v220|
	v_fma_f32 v228, |v227|, v228, |v227|
	v_fma_f32 v235, |v234|, v235, |v234|
	v_mul_f32_e32 v216, s19, v214
	v_mul_f32_e32 v223, s19, v221
	v_mul_f32_e32 v230, s19, v228
	v_mul_f32_e32 v237, s19, v235
	v_fma_f32 v217, v214, s19, -v216
	v_fma_f32 v224, v221, s19, -v223
	v_fma_f32 v231, v228, s19, -v230
	v_fma_f32 v238, v235, s19, -v237
	v_rndne_f32_e32 v218, v216
	v_rndne_f32_e32 v225, v223
	v_rndne_f32_e32 v232, v230
	v_rndne_f32_e32 v239, v237
	v_fmac_f32_e32 v217, 0xb2a5705f, v214
	v_fmac_f32_e32 v224, 0xb2a5705f, v221
	v_fmac_f32_e32 v231, 0xb2a5705f, v228
	v_fmac_f32_e32 v238, 0xb2a5705f, v235
	v_sub_f32_e32 v216, v216, v218
	v_sub_f32_e32 v223, v223, v225
	v_sub_f32_e32 v230, v230, v232
	v_sub_f32_e32 v237, v237, v239
	v_add_f32_e32 v216, v216, v217
	v_add_f32_e32 v223, v223, v224
	v_add_f32_e32 v230, v230, v231
	v_add_f32_e32 v237, v237, v238
	v_cvt_i32_f32_e32 v218, v218
	v_cvt_i32_f32_e32 v225, v225
	v_cvt_i32_f32_e32 v232, v232
	v_cvt_i32_f32_e32 v239, v239
	v_exp_f32_e32 v216, v216
	v_exp_f32_e32 v223, v223
	v_exp_f32_e32 v230, v230
	v_exp_f32_e32 v237, v237
	v_cmp_nlt_f32_e64 s[4:5], s20, v214
	v_cmp_nlt_f32_e64 s[98:99], s20, v221
	v_cmp_nlt_f32_e64 s[100:101], s20, v228
	v_cmp_nlt_f32_e64 vcc, s20, v235
	v_ldexp_f32 v216, v216, v218
	v_ldexp_f32 v223, v223, v225
	v_ldexp_f32 v230, v230, v232
	v_ldexp_f32 v237, v237, v239
	v_mul_f32_e32 v215, v213, v213
	v_mul_f32_e32 v222, v220, v220
	v_mul_f32_e32 v229, v227, v227
	v_mul_f32_e32 v236, v234, v234
	v_cndmask_b32_e64 v216, 0, v216, s[4:5]
	v_cndmask_b32_e64 v223, 0, v223, s[98:99]
	v_cndmask_b32_e64 v230, 0, v230, s[100:101]
	v_cndmask_b32_e64 v237, 0, v237, vcc
	v_cmp_ngt_f32_e64 s[4:5], s21, v214
	v_cmp_ngt_f32_e64 s[98:99], s21, v221
	v_cmp_ngt_f32_e64 s[100:101], s21, v228
	v_cmp_ngt_f32_e64 vcc, s21, v235
	v_fmamk_f32 v217, v215, 0xba1345e1, v195
	v_fmamk_f32 v224, v222, 0xba1345e1, v195
	v_fmamk_f32 v231, v229, 0xba1345e1, v195
	v_fmamk_f32 v238, v236, 0xba1345e1, v195
	v_fmaak_f32 v217, v215, v217, 0xbcdac9b8
	v_fmaak_f32 v224, v222, v224, 0xbcdac9b8
	v_fmaak_f32 v231, v229, v231, 0xbcdac9b8
	v_fmaak_f32 v238, v236, v238, 0xbcdac9b8
	v_cndmask_b32_e64 v216, v194, v216, s[4:5]
	v_cndmask_b32_e64 v223, v194, v223, s[98:99]
	v_cndmask_b32_e64 v230, v194, v230, s[100:101]
	v_cndmask_b32_e64 v237, v194, v237, vcc
	v_fmaak_f32 v217, v215, v217, 0x3de703be
	v_fmaak_f32 v224, v222, v224, 0x3de703be
	v_fmaak_f32 v231, v229, v231, 0x3de703be
	v_fmaak_f32 v238, v236, v238, 0x3de703be
	v_fmaak_f32 v217, v215, v217, 0xbec09330
	v_fmaak_f32 v224, v222, v224, 0xbec09330
	v_fmaak_f32 v231, v229, v231, 0xbec09330
	v_fmaak_f32 v238, v236, v238, 0xbec09330
	v_sub_f32_e32 v216, 1.0, v216
	v_sub_f32_e32 v223, 1.0, v223
	v_sub_f32_e32 v230, 1.0, v230
	v_sub_f32_e32 v237, 1.0, v237
	v_fmaak_f32 v217, v215, v217, 0x3e0375d0
	v_fmaak_f32 v224, v222, v224, 0x3e0375d0
	v_fmaak_f32 v231, v229, v231, 0x3e0375d0
	v_fmaak_f32 v238, v236, v238, 0x3e0375d0
	v_cmp_nlt_f32_e64 s[4:5], |v213|, 1.0
	v_cmp_nlt_f32_e64 s[98:99], |v220|, 1.0
	v_cmp_nlt_f32_e64 s[100:101], |v227|, 1.0
	v_cmp_nlt_f32_e64 vcc, |v234|, 1.0
	v_fma_f32 v217, |v213|, v217, |v213|
	v_fma_f32 v224, |v220|, v224, |v220|
	v_fma_f32 v231, |v227|, v231, |v227|
	v_fma_f32 v238, |v234|, v238, |v234|
	v_mul_f32_e32 v212, 0.5, v212
	v_mul_f32_e32 v219, 0.5, v219
	v_mul_f32_e32 v226, 0.5, v226
	v_mul_f32_e32 v233, 0.5, v233
	v_mul_f32_e32 v215, v128, v120
	v_mul_f32_e32 v222, v129, v121
	v_mul_f32_e32 v229, v130, v122
	v_mul_f32_e32 v236, v131, v123
	v_cndmask_b32_e64 v216, v217, v216, s[4:5]
	v_cndmask_b32_e64 v223, v224, v223, s[98:99]
	v_cndmask_b32_e64 v230, v231, v230, s[100:101]
	v_cndmask_b32_e64 v237, v238, v237, vcc
	v_bfi_b32 v216, s22, v216, v213
	v_bfi_b32 v223, s22, v223, v220
	v_bfi_b32 v230, s22, v230, v227
	v_bfi_b32 v237, s22, v237, v234
	v_add_f32_e32 v216, 1.0, v216
	v_add_f32_e32 v223, 1.0, v223
	v_add_f32_e32 v230, 1.0, v230
	v_add_f32_e32 v237, 1.0, v237
	v_mul_f32_e32 v212, v212, v216
	v_mul_f32_e32 v219, v219, v223
	v_mul_f32_e32 v226, v226, v230
	v_mul_f32_e32 v233, v233, v237
	v_mul_f32_e32 v212, v128, v212
	v_mul_f32_e32 v219, v129, v219
	v_mul_f32_e32 v226, v130, v226
	v_mul_f32_e32 v233, v131, v233
	v_mul_f32_e32 v240, v120, v212
	v_mul_f32_e32 v241, v121, v219
	v_mul_f32_e32 v242, v122, v226
	v_mul_f32_e32 v243, v123, v233
	global_store_dwordx4 v250, v[240:243], s[94:95]
	v_add_u32_e32 v250, 0x200000, v250
	s_add_u32 s17, s17, 1
	s_cmp_lt_u32 s17, s16
	s_cbranch_scc0 .Lact0_done
	s_waitcnt vmcnt(24)
	v_lshlrev_b32_e32 v196, 2, v96
	v_lshlrev_b32_e32 v197, 2, v97
	v_lshlrev_b32_e32 v198, 2, v98
	v_lshlrev_b32_e32 v199, 2, v99
	ds_read_b32 v112, v196
	ds_read_b32 v113, v197
	ds_read_b32 v114, v198
	ds_read_b32 v115, v199
	global_load_dword v120, v196, s[26:27]
	global_load_dword v121, v197, s[26:27]
	global_load_dword v122, v198, s[26:27]
	global_load_dword v123, v199, s[26:27]
	global_load_dwordx4 v[128:131], v248, s[94:95]
	v_add_u32_e32 v248, 0x200000, v248
	v_min_u32_e32 v248, v248, v249
	global_load_dwordx4 v[104:107], v246, s[94:95]
	v_add_u32_e32 v246, 0x200000, v246
	v_min_u32_e32 v246, v246, v247
	global_load_dwordx4 v[0:3], v244, s[94:95]
	v_add_u32_e32 v251, 0x2040000, v244
	global_load_dwordx4 v[4:7], v251, s[94:95]
	v_add_u32_e32 v251, 0x4080000, v244
	global_load_dwordx4 v[8:11], v251, s[94:95]
	v_add_u32_e32 v251, 0x60c0000, v244
	global_load_dwordx4 v[12:15], v251, s[94:95]
	v_add_u32_e32 v251, 0x8100000, v244
	global_load_dwordx4 v[16:19], v251, s[94:95]
	v_add_u32_e32 v251, 0xa140000, v244
	global_load_dwordx4 v[20:23], v251, s[94:95]
	v_add_u32_e32 v251, 0xc180000, v244
	global_load_dwordx4 v[24:27], v251, s[94:95]
	v_add_u32_e32 v251, 0xe1c0000, v244
	global_load_dwordx4 v[28:31], v251, s[94:95]
	v_add_u32_e32 v244, 0x200000, v244
	v_min_u32_e32 v244, v244, v245
	s_waitcnt vmcnt(24) lgkmcnt(4)
	v_add_f32_e32 v212, 0, v32
	v_add_f32_e32 v219, 0, v33
	v_add_f32_e32 v226, 0, v34
	v_add_f32_e32 v233, 0, v35
	v_add_f32_e32 v212, v212, v36
	v_add_f32_e32 v219, v219, v37
	v_add_f32_e32 v226, v226, v38
	v_add_f32_e32 v233, v233, v39
	v_add_f32_e32 v212, v212, v40
	v_add_f32_e32 v219, v219, v41
	v_add_f32_e32 v226, v226, v42
	v_add_f32_e32 v233, v233, v43
	v_add_f32_e32 v212, v212, v44
	v_add_f32_e32 v219, v219, v45
	v_add_f32_e32 v226, v226, v46
	v_add_f32_e32 v233, v233, v47
	v_add_f32_e32 v212, v212, v48
	v_add_f32_e32 v219, v219, v49
	v_add_f32_e32 v226, v226, v50
	v_add_f32_e32 v233, v233, v51
	v_add_f32_e32 v212, v212, v52
	v_add_f32_e32 v219, v219, v53
	v_add_f32_e32 v226, v226, v54
	v_add_f32_e32 v233, v233, v55
	v_add_f32_e32 v212, v212, v56
	v_add_f32_e32 v219, v219, v57
	v_add_f32_e32 v226, v226, v58
	v_add_f32_e32 v233, v233, v59
	v_add_f32_e32 v212, v212, v60
	v_add_f32_e32 v219, v219, v61
	v_add_f32_e32 v226, v226, v62
	v_add_f32_e32 v233, v233, v63
	v_mul_f32_e32 v212, v212, v116
	v_mul_f32_e32 v219, v219, v117
	v_mul_f32_e32 v226, v226, v118
	v_mul_f32_e32 v233, v233, v119
	v_mul_f32_e32 v213, 0x3f3504f3, v212
	v_mul_f32_e32 v220, 0x3f3504f3, v219
	v_mul_f32_e32 v227, 0x3f3504f3, v226
	v_mul_f32_e32 v234, 0x3f3504f3, v233
	v_fma_f32 v214, |v213|, v187, v188
	v_fma_f32 v221, |v220|, v187, v188
	v_fma_f32 v228, |v227|, v187, v188
	v_fma_f32 v235, |v234|, v187, v188
	v_fma_f32 v214, |v213|, v214, v189
	v_fma_f32 v221, |v220|, v221, v189
	v_fma_f32 v228, |v227|, v228, v189
	v_fma_f32 v235, |v234|, v235, v189
	v_fma_f32 v214, |v213|, v214, v190
	v_fma_f32 v221, |v220|, v221, v190
	v_fma_f32 v228, |v227|, v228, v190
	v_fma_f32 v235, |v234|, v235, v190
	v_fma_f32 v214, |v213|, v214, v191
	v_fma_f32 v221, |v220|, v221, v191
	v_fma_f32 v228, |v227|, v228, v191
	v_fma_f32 v235, |v234|, v235, v191
	v_fma_f32 v214, |v213|, v214, v192
	v_fma_f32 v221, |v220|, v221, v192
	v_fma_f32 v228, |v227|, v228, v192
	v_fma_f32 v235, |v234|, v235, v192
	v_fma_f32 v214, |v213|, v214, v193
	v_fma_f32 v221, |v220|, v221, v193
	v_fma_f32 v228, |v227|, v228, v193
	v_fma_f32 v235, |v234|, v235, v193
	v_fma_f32 v214, |v213|, v214, |v213|
	v_fma_f32 v221, |v220|, v221, |v220|
	v_fma_f32 v228, |v227|, v228, |v227|
	v_fma_f32 v235, |v234|, v235, |v234|
	v_mul_f32_e32 v216, s19, v214
	v_mul_f32_e32 v223, s19, v221
	v_mul_f32_e32 v230, s19, v228
	v_mul_f32_e32 v237, s19, v235
	v_fma_f32 v217, v214, s19, -v216
	v_fma_f32 v224, v221, s19, -v223
	v_fma_f32 v231, v228, s19, -v230
	v_fma_f32 v238, v235, s19, -v237
	v_rndne_f32_e32 v218, v216
	v_rndne_f32_e32 v225, v223
	v_rndne_f32_e32 v232, v230
	v_rndne_f32_e32 v239, v237
	v_fmac_f32_e32 v217, 0xb2a5705f, v214
	v_fmac_f32_e32 v224, 0xb2a5705f, v221
	v_fmac_f32_e32 v231, 0xb2a5705f, v228
	v_fmac_f32_e32 v238, 0xb2a5705f, v235
	v_sub_f32_e32 v216, v216, v218
	v_sub_f32_e32 v223, v223, v225
	v_sub_f32_e32 v230, v230, v232
	v_sub_f32_e32 v237, v237, v239
	v_add_f32_e32 v216, v216, v217
	v_add_f32_e32 v223, v223, v224
	v_add_f32_e32 v230, v230, v231
	v_add_f32_e32 v237, v237, v238
	v_cvt_i32_f32_e32 v218, v218
	v_cvt_i32_f32_e32 v225, v225
	v_cvt_i32_f32_e32 v232, v232
	v_cvt_i32_f32_e32 v239, v239
	v_exp_f32_e32 v216, v216
	v_exp_f32_e32 v223, v223
	v_exp_f32_e32 v230, v230
	v_exp_f32_e32 v237, v237
	v_cmp_nlt_f32_e64 s[4:5], s20, v214
	v_cmp_nlt_f32_e64 s[98:99], s20, v221
	v_cmp_nlt_f32_e64 s[100:101], s20, v228
	v_cmp_nlt_f32_e64 vcc, s20, v235
	v_ldexp_f32 v216, v216, v218
	v_ldexp_f32 v223, v223, v225
	v_ldexp_f32 v230, v230, v232
	v_ldexp_f32 v237, v237, v239
	v_mul_f32_e32 v215, v213, v213
	v_mul_f32_e32 v222, v220, v220
	v_mul_f32_e32 v229, v227, v227
	v_mul_f32_e32 v236, v234, v234
	v_cndmask_b32_e64 v216, 0, v216, s[4:5]
	v_cndmask_b32_e64 v223, 0, v223, s[98:99]
	v_cndmask_b32_e64 v230, 0, v230, s[100:101]
	v_cndmask_b32_e64 v237, 0, v237, vcc
	v_cmp_ngt_f32_e64 s[4:5], s21, v214
	v_cmp_ngt_f32_e64 s[98:99], s21, v221
	v_cmp_ngt_f32_e64 s[100:101], s21, v228
	v_cmp_ngt_f32_e64 vcc, s21, v235
	v_fmamk_f32 v217, v215, 0xba1345e1, v195
	v_fmamk_f32 v224, v222, 0xba1345e1, v195
	v_fmamk_f32 v231, v229, 0xba1345e1, v195
	v_fmamk_f32 v238, v236, 0xba1345e1, v195
	v_fmaak_f32 v217, v215, v217, 0xbcdac9b8
	v_fmaak_f32 v224, v222, v224, 0xbcdac9b8
	v_fmaak_f32 v231, v229, v231, 0xbcdac9b8
	v_fmaak_f32 v238, v236, v238, 0xbcdac9b8
	v_cndmask_b32_e64 v216, v194, v216, s[4:5]
	v_cndmask_b32_e64 v223, v194, v223, s[98:99]
	v_cndmask_b32_e64 v230, v194, v230, s[100:101]
	v_cndmask_b32_e64 v237, v194, v237, vcc
	v_fmaak_f32 v217, v215, v217, 0x3de703be
	v_fmaak_f32 v224, v222, v224, 0x3de703be
	v_fmaak_f32 v231, v229, v231, 0x3de703be
	v_fmaak_f32 v238, v236, v238, 0x3de703be
	v_fmaak_f32 v217, v215, v217, 0xbec09330
	v_fmaak_f32 v224, v222, v224, 0xbec09330
	v_fmaak_f32 v231, v229, v231, 0xbec09330
	v_fmaak_f32 v238, v236, v238, 0xbec09330
	v_sub_f32_e32 v216, 1.0, v216
	v_sub_f32_e32 v223, 1.0, v223
	v_sub_f32_e32 v230, 1.0, v230
	v_sub_f32_e32 v237, 1.0, v237
	v_fmaak_f32 v217, v215, v217, 0x3e0375d0
	v_fmaak_f32 v224, v222, v224, 0x3e0375d0
	v_fmaak_f32 v231, v229, v231, 0x3e0375d0
	v_fmaak_f32 v238, v236, v238, 0x3e0375d0
	v_cmp_nlt_f32_e64 s[4:5], |v213|, 1.0
	v_cmp_nlt_f32_e64 s[98:99], |v220|, 1.0
	v_cmp_nlt_f32_e64 s[100:101], |v227|, 1.0
	v_cmp_nlt_f32_e64 vcc, |v234|, 1.0
	v_fma_f32 v217, |v213|, v217, |v213|
	v_fma_f32 v224, |v220|, v224, |v220|
	v_fma_f32 v231, |v227|, v231, |v227|
	v_fma_f32 v238, |v234|, v238, |v234|
	v_mul_f32_e32 v212, 0.5, v212
	v_mul_f32_e32 v219, 0.5, v219
	v_mul_f32_e32 v226, 0.5, v226
	v_mul_f32_e32 v233, 0.5, v233
	v_mul_f32_e32 v215, v132, v124
	v_mul_f32_e32 v222, v133, v125
	v_mul_f32_e32 v229, v134, v126
	v_mul_f32_e32 v236, v135, v127
	v_cndmask_b32_e64 v216, v217, v216, s[4:5]
	v_cndmask_b32_e64 v223, v224, v223, s[98:99]
	v_cndmask_b32_e64 v230, v231, v230, s[100:101]
	v_cndmask_b32_e64 v237, v238, v237, vcc
	v_bfi_b32 v216, s22, v216, v213
	v_bfi_b32 v223, s22, v223, v220
	v_bfi_b32 v230, s22, v230, v227
	v_bfi_b32 v237, s22, v237, v234
	v_add_f32_e32 v216, 1.0, v216
	v_add_f32_e32 v223, 1.0, v223
	v_add_f32_e32 v230, 1.0, v230
	v_add_f32_e32 v237, 1.0, v237
	v_mul_f32_e32 v212, v212, v216
	v_mul_f32_e32 v219, v219, v223
	v_mul_f32_e32 v226, v226, v230
	v_mul_f32_e32 v233, v233, v237
	v_mul_f32_e32 v212, v132, v212
	v_mul_f32_e32 v219, v133, v219
	v_mul_f32_e32 v226, v134, v226
	v_mul_f32_e32 v233, v135, v233
	v_mul_f32_e32 v240, v124, v212
	v_mul_f32_e32 v241, v125, v219
	v_mul_f32_e32 v242, v126, v226
	v_mul_f32_e32 v243, v127, v233
	global_store_dwordx4 v250, v[240:243], s[94:95]
	v_add_u32_e32 v250, 0x200000, v250
	s_add_u32 s17, s17, 1
	s_cmp_lt_u32 s17, s16
	s_cbranch_scc0 .Lact0_done
	s_waitcnt vmcnt(24)
	v_lshlrev_b32_e32 v196, 2, v100
	v_lshlrev_b32_e32 v197, 2, v101
	v_lshlrev_b32_e32 v198, 2, v102
	v_lshlrev_b32_e32 v199, 2, v103
	ds_read_b32 v116, v196
	ds_read_b32 v117, v197
	ds_read_b32 v118, v198
	ds_read_b32 v119, v199
	global_load_dword v124, v196, s[26:27]
	global_load_dword v125, v197, s[26:27]
	global_load_dword v126, v198, s[26:27]
	global_load_dword v127, v199, s[26:27]
	global_load_dwordx4 v[132:135], v248, s[94:95]
	v_add_u32_e32 v248, 0x200000, v248
	v_min_u32_e32 v248, v248, v249
	global_load_dwordx4 v[108:111], v246, s[94:95]
	v_add_u32_e32 v246, 0x200000, v246
	v_min_u32_e32 v246, v246, v247
	global_load_dwordx4 v[32:35], v244, s[94:95]
	v_add_u32_e32 v251, 0x2040000, v244
	global_load_dwordx4 v[36:39], v251, s[94:95]
	v_add_u32_e32 v251, 0x4080000, v244
	global_load_dwordx4 v[40:43], v251, s[94:95]
	v_add_u32_e32 v251, 0x60c0000, v244
	global_load_dwordx4 v[44:47], v251, s[94:95]
	v_add_u32_e32 v251, 0x8100000, v244
	global_load_dwordx4 v[48:51], v251, s[94:95]
	v_add_u32_e32 v251, 0xa140000, v244
	global_load_dwordx4 v[52:55], v251, s[94:95]
	v_add_u32_e32 v251, 0xc180000, v244
	global_load_dwordx4 v[56:59], v251, s[94:95]
	v_add_u32_e32 v251, 0xe1c0000, v244
	global_load_dwordx4 v[60:63], v251, s[94:95]
	v_add_u32_e32 v244, 0x200000, v244
	v_min_u32_e32 v244, v244, v245
	s_waitcnt vmcnt(24) lgkmcnt(4)
	v_add_f32_e32 v212, 0, v64
	v_add_f32_e32 v219, 0, v65
	v_add_f32_e32 v226, 0, v66
	v_add_f32_e32 v233, 0, v67
	v_add_f32_e32 v212, v212, v68
	v_add_f32_e32 v219, v219, v69
	v_add_f32_e32 v226, v226, v70
	v_add_f32_e32 v233, v233, v71
	v_add_f32_e32 v212, v212, v72
	v_add_f32_e32 v219, v219, v73
	v_add_f32_e32 v226, v226, v74
	v_add_f32_e32 v233, v233, v75
	v_add_f32_e32 v212, v212, v76
	v_add_f32_e32 v219, v219, v77
	v_add_f32_e32 v226, v226, v78
	v_add_f32_e32 v233, v233, v79
	v_add_f32_e32 v212, v212, v80
	v_add_f32_e32 v219, v219, v81
	v_add_f32_e32 v226, v226, v82
	v_add_f32_e32 v233, v233, v83
	v_add_f32_e32 v212, v212, v84
	v_add_f32_e32 v219, v219, v85
	v_add_f32_e32 v226, v226, v86
	v_add_f32_e32 v233, v233, v87
	v_add_f32_e32 v212, v212, v88
	v_add_f32_e32 v219, v219, v89
	v_add_f32_e32 v226, v226, v90
	v_add_f32_e32 v233, v233, v91
	v_add_f32_e32 v212, v212, v92
	v_add_f32_e32 v219, v219, v93
	v_add_f32_e32 v226, v226, v94
	v_add_f32_e32 v233, v233, v95
	v_mul_f32_e32 v212, v212, v112
	v_mul_f32_e32 v219, v219, v113
	v_mul_f32_e32 v226, v226, v114
	v_mul_f32_e32 v233, v233, v115
	v_mul_f32_e32 v213, 0x3f3504f3, v212
	v_mul_f32_e32 v220, 0x3f3504f3, v219
	v_mul_f32_e32 v227, 0x3f3504f3, v226
	v_mul_f32_e32 v234, 0x3f3504f3, v233
	v_fma_f32 v214, |v213|, v187, v188
	v_fma_f32 v221, |v220|, v187, v188
	v_fma_f32 v228, |v227|, v187, v188
	v_fma_f32 v235, |v234|, v187, v188
	v_fma_f32 v214, |v213|, v214, v189
	v_fma_f32 v221, |v220|, v221, v189
	v_fma_f32 v228, |v227|, v228, v189
	v_fma_f32 v235, |v234|, v235, v189
	v_fma_f32 v214, |v213|, v214, v190
	v_fma_f32 v221, |v220|, v221, v190
	v_fma_f32 v228, |v227|, v228, v190
	v_fma_f32 v235, |v234|, v235, v190
	v_fma_f32 v214, |v213|, v214, v191
	v_fma_f32 v221, |v220|, v221, v191
	v_fma_f32 v228, |v227|, v228, v191
	v_fma_f32 v235, |v234|, v235, v191
	v_fma_f32 v214, |v213|, v214, v192
	v_fma_f32 v221, |v220|, v221, v192
	v_fma_f32 v228, |v227|, v228, v192
	v_fma_f32 v235, |v234|, v235, v192
	v_fma_f32 v214, |v213|, v214, v193
	v_fma_f32 v221, |v220|, v221, v193
	v_fma_f32 v228, |v227|, v228, v193
	v_fma_f32 v235, |v234|, v235, v193
	v_fma_f32 v214, |v213|, v214, |v213|
	v_fma_f32 v221, |v220|, v221, |v220|
	v_fma_f32 v228, |v227|, v228, |v227|
	v_fma_f32 v235, |v234|, v235, |v234|
	v_mul_f32_e32 v216, s19, v214
	v_mul_f32_e32 v223, s19, v221
	v_mul_f32_e32 v230, s19, v228
	v_mul_f32_e32 v237, s19, v235
	v_fma_f32 v217, v214, s19, -v216
	v_fma_f32 v224, v221, s19, -v223
	v_fma_f32 v231, v228, s19, -v230
	v_fma_f32 v238, v235, s19, -v237
	v_rndne_f32_e32 v218, v216
	v_rndne_f32_e32 v225, v223
	v_rndne_f32_e32 v232, v230
	v_rndne_f32_e32 v239, v237
	v_fmac_f32_e32 v217, 0xb2a5705f, v214
	v_fmac_f32_e32 v224, 0xb2a5705f, v221
	v_fmac_f32_e32 v231, 0xb2a5705f, v228
	v_fmac_f32_e32 v238, 0xb2a5705f, v235
	v_sub_f32_e32 v216, v216, v218
	v_sub_f32_e32 v223, v223, v225
	v_sub_f32_e32 v230, v230, v232
	v_sub_f32_e32 v237, v237, v239
	v_add_f32_e32 v216, v216, v217
	v_add_f32_e32 v223, v223, v224
	v_add_f32_e32 v230, v230, v231
	v_add_f32_e32 v237, v237, v238
	v_cvt_i32_f32_e32 v218, v218
	v_cvt_i32_f32_e32 v225, v225
	v_cvt_i32_f32_e32 v232, v232
	v_cvt_i32_f32_e32 v239, v239
	v_exp_f32_e32 v216, v216
	v_exp_f32_e32 v223, v223
	v_exp_f32_e32 v230, v230
	v_exp_f32_e32 v237, v237
	v_cmp_nlt_f32_e64 s[4:5], s20, v214
	v_cmp_nlt_f32_e64 s[98:99], s20, v221
	v_cmp_nlt_f32_e64 s[100:101], s20, v228
	v_cmp_nlt_f32_e64 vcc, s20, v235
	v_ldexp_f32 v216, v216, v218
	v_ldexp_f32 v223, v223, v225
	v_ldexp_f32 v230, v230, v232
	v_ldexp_f32 v237, v237, v239
	v_mul_f32_e32 v215, v213, v213
	v_mul_f32_e32 v222, v220, v220
	v_mul_f32_e32 v229, v227, v227
	v_mul_f32_e32 v236, v234, v234
	v_cndmask_b32_e64 v216, 0, v216, s[4:5]
	v_cndmask_b32_e64 v223, 0, v223, s[98:99]
	v_cndmask_b32_e64 v230, 0, v230, s[100:101]
	v_cndmask_b32_e64 v237, 0, v237, vcc
	v_cmp_ngt_f32_e64 s[4:5], s21, v214
	v_cmp_ngt_f32_e64 s[98:99], s21, v221
	v_cmp_ngt_f32_e64 s[100:101], s21, v228
	v_cmp_ngt_f32_e64 vcc, s21, v235
	v_fmamk_f32 v217, v215, 0xba1345e1, v195
	v_fmamk_f32 v224, v222, 0xba1345e1, v195
	v_fmamk_f32 v231, v229, 0xba1345e1, v195
	v_fmamk_f32 v238, v236, 0xba1345e1, v195
	v_fmaak_f32 v217, v215, v217, 0xbcdac9b8
	v_fmaak_f32 v224, v222, v224, 0xbcdac9b8
	v_fmaak_f32 v231, v229, v231, 0xbcdac9b8
	v_fmaak_f32 v238, v236, v238, 0xbcdac9b8
	v_cndmask_b32_e64 v216, v194, v216, s[4:5]
	v_cndmask_b32_e64 v223, v194, v223, s[98:99]
	v_cndmask_b32_e64 v230, v194, v230, s[100:101]
	v_cndmask_b32_e64 v237, v194, v237, vcc
	v_fmaak_f32 v217, v215, v217, 0x3de703be
	v_fmaak_f32 v224, v222, v224, 0x3de703be
	v_fmaak_f32 v231, v229, v231, 0x3de703be
	v_fmaak_f32 v238, v236, v238, 0x3de703be
	v_fmaak_f32 v217, v215, v217, 0xbec09330
	v_fmaak_f32 v224, v222, v224, 0xbec09330
	v_fmaak_f32 v231, v229, v231, 0xbec09330
	v_fmaak_f32 v238, v236, v238, 0xbec09330
	v_sub_f32_e32 v216, 1.0, v216
	v_sub_f32_e32 v223, 1.0, v223
	v_sub_f32_e32 v230, 1.0, v230
	v_sub_f32_e32 v237, 1.0, v237
	v_fmaak_f32 v217, v215, v217, 0x3e0375d0
	v_fmaak_f32 v224, v222, v224, 0x3e0375d0
	v_fmaak_f32 v231, v229, v231, 0x3e0375d0
	v_fmaak_f32 v238, v236, v238, 0x3e0375d0
	v_cmp_nlt_f32_e64 s[4:5], |v213|, 1.0
	v_cmp_nlt_f32_e64 s[98:99], |v220|, 1.0
	v_cmp_nlt_f32_e64 s[100:101], |v227|, 1.0
	v_cmp_nlt_f32_e64 vcc, |v234|, 1.0
	v_fma_f32 v217, |v213|, v217, |v213|
	v_fma_f32 v224, |v220|, v224, |v220|
	v_fma_f32 v231, |v227|, v231, |v227|
	v_fma_f32 v238, |v234|, v238, |v234|
	v_mul_f32_e32 v212, 0.5, v212
	v_mul_f32_e32 v219, 0.5, v219
	v_mul_f32_e32 v226, 0.5, v226
	v_mul_f32_e32 v233, 0.5, v233
	v_mul_f32_e32 v215, v128, v120
	v_mul_f32_e32 v222, v129, v121
	v_mul_f32_e32 v229, v130, v122
	v_mul_f32_e32 v236, v131, v123
	v_cndmask_b32_e64 v216, v217, v216, s[4:5]
	v_cndmask_b32_e64 v223, v224, v223, s[98:99]
	v_cndmask_b32_e64 v230, v231, v230, s[100:101]
	v_cndmask_b32_e64 v237, v238, v237, vcc
	v_bfi_b32 v216, s22, v216, v213
	v_bfi_b32 v223, s22, v223, v220
	v_bfi_b32 v230, s22, v230, v227
	v_bfi_b32 v237, s22, v237, v234
	v_add_f32_e32 v216, 1.0, v216
	v_add_f32_e32 v223, 1.0, v223
	v_add_f32_e32 v230, 1.0, v230
	v_add_f32_e32 v237, 1.0, v237
	v_mul_f32_e32 v212, v212, v216
	v_mul_f32_e32 v219, v219, v223
	v_mul_f32_e32 v226, v226, v230
	v_mul_f32_e32 v233, v233, v237
	v_mul_f32_e32 v212, v128, v212
	v_mul_f32_e32 v219, v129, v219
	v_mul_f32_e32 v226, v130, v226
	v_mul_f32_e32 v233, v131, v233
	v_mul_f32_e32 v240, v120, v212
	v_mul_f32_e32 v241, v121, v219
	v_mul_f32_e32 v242, v122, v226
	v_mul_f32_e32 v243, v123, v233
	global_store_dwordx4 v250, v[240:243], s[94:95]
	v_add_u32_e32 v250, 0x200000, v250
	s_add_u32 s17, s17, 1
	s_cmp_lt_u32 s17, s16
	s_cbranch_scc0 .Lact0_done
	s_waitcnt vmcnt(24)
	v_lshlrev_b32_e32 v196, 2, v104
	v_lshlrev_b32_e32 v197, 2, v105
	v_lshlrev_b32_e32 v198, 2, v106
	v_lshlrev_b32_e32 v199, 2, v107
	ds_read_b32 v112, v196
	ds_read_b32 v113, v197
	ds_read_b32 v114, v198
	ds_read_b32 v115, v199
	global_load_dword v120, v196, s[26:27]
	global_load_dword v121, v197, s[26:27]
	global_load_dword v122, v198, s[26:27]
	global_load_dword v123, v199, s[26:27]
	global_load_dwordx4 v[128:131], v248, s[94:95]
	v_add_u32_e32 v248, 0x200000, v248
	v_min_u32_e32 v248, v248, v249
	global_load_dwordx4 v[96:99], v246, s[94:95]
	v_add_u32_e32 v246, 0x200000, v246
	v_min_u32_e32 v246, v246, v247
	global_load_dwordx4 v[64:67], v244, s[94:95]
	v_add_u32_e32 v251, 0x2040000, v244
	global_load_dwordx4 v[68:71], v251, s[94:95]
	v_add_u32_e32 v251, 0x4080000, v244
	global_load_dwordx4 v[72:75], v251, s[94:95]
	v_add_u32_e32 v251, 0x60c0000, v244
	global_load_dwordx4 v[76:79], v251, s[94:95]
	v_add_u32_e32 v251, 0x8100000, v244
	global_load_dwordx4 v[80:83], v251, s[94:95]
	v_add_u32_e32 v251, 0xa140000, v244
	global_load_dwordx4 v[84:87], v251, s[94:95]
	v_add_u32_e32 v251, 0xc180000, v244
	global_load_dwordx4 v[88:91], v251, s[94:95]
	v_add_u32_e32 v251, 0xe1c0000, v244
	global_load_dwordx4 v[92:95], v251, s[94:95]
	v_add_u32_e32 v244, 0x200000, v244
	v_min_u32_e32 v244, v244, v245
	s_waitcnt vmcnt(24) lgkmcnt(4)
	v_add_f32_e32 v212, 0, v0
	v_add_f32_e32 v219, 0, v1
	v_add_f32_e32 v226, 0, v2
	v_add_f32_e32 v233, 0, v3
	v_add_f32_e32 v212, v212, v4
	v_add_f32_e32 v219, v219, v5
	v_add_f32_e32 v226, v226, v6
	v_add_f32_e32 v233, v233, v7
	v_add_f32_e32 v212, v212, v8
	v_add_f32_e32 v219, v219, v9
	v_add_f32_e32 v226, v226, v10
	v_add_f32_e32 v233, v233, v11
	v_add_f32_e32 v212, v212, v12
	v_add_f32_e32 v219, v219, v13
	v_add_f32_e32 v226, v226, v14
	v_add_f32_e32 v233, v233, v15
	v_add_f32_e32 v212, v212, v16
	v_add_f32_e32 v219, v219, v17
	v_add_f32_e32 v226, v226, v18
	v_add_f32_e32 v233, v233, v19
	v_add_f32_e32 v212, v212, v20
	v_add_f32_e32 v219, v219, v21
	v_add_f32_e32 v226, v226, v22
	v_add_f32_e32 v233, v233, v23
	v_add_f32_e32 v212, v212, v24
	v_add_f32_e32 v219, v219, v25
	v_add_f32_e32 v226, v226, v26
	v_add_f32_e32 v233, v233, v27
	v_add_f32_e32 v212, v212, v28
	v_add_f32_e32 v219, v219, v29
	v_add_f32_e32 v226, v226, v30
	v_add_f32_e32 v233, v233, v31
	v_mul_f32_e32 v212, v212, v116
	v_mul_f32_e32 v219, v219, v117
	v_mul_f32_e32 v226, v226, v118
	v_mul_f32_e32 v233, v233, v119
	v_mul_f32_e32 v213, 0x3f3504f3, v212
	v_mul_f32_e32 v220, 0x3f3504f3, v219
	v_mul_f32_e32 v227, 0x3f3504f3, v226
	v_mul_f32_e32 v234, 0x3f3504f3, v233
	v_fma_f32 v214, |v213|, v187, v188
	v_fma_f32 v221, |v220|, v187, v188
	v_fma_f32 v228, |v227|, v187, v188
	v_fma_f32 v235, |v234|, v187, v188
	v_fma_f32 v214, |v213|, v214, v189
	v_fma_f32 v221, |v220|, v221, v189
	v_fma_f32 v228, |v227|, v228, v189
	v_fma_f32 v235, |v234|, v235, v189
	v_fma_f32 v214, |v213|, v214, v190
	v_fma_f32 v221, |v220|, v221, v190
	v_fma_f32 v228, |v227|, v228, v190
	v_fma_f32 v235, |v234|, v235, v190
	v_fma_f32 v214, |v213|, v214, v191
	v_fma_f32 v221, |v220|, v221, v191
	v_fma_f32 v228, |v227|, v228, v191
	v_fma_f32 v235, |v234|, v235, v191
	v_fma_f32 v214, |v213|, v214, v192
	v_fma_f32 v221, |v220|, v221, v192
	v_fma_f32 v228, |v227|, v228, v192
	v_fma_f32 v235, |v234|, v235, v192
	v_fma_f32 v214, |v213|, v214, v193
	v_fma_f32 v221, |v220|, v221, v193
	v_fma_f32 v228, |v227|, v228, v193
	v_fma_f32 v235, |v234|, v235, v193
	v_fma_f32 v214, |v213|, v214, |v213|
	v_fma_f32 v221, |v220|, v221, |v220|
	v_fma_f32 v228, |v227|, v228, |v227|
	v_fma_f32 v235, |v234|, v235, |v234|
	v_mul_f32_e32 v216, s19, v214
	v_mul_f32_e32 v223, s19, v221
	v_mul_f32_e32 v230, s19, v228
	v_mul_f32_e32 v237, s19, v235
	v_fma_f32 v217, v214, s19, -v216
	v_fma_f32 v224, v221, s19, -v223
	v_fma_f32 v231, v228, s19, -v230
	v_fma_f32 v238, v235, s19, -v237
	v_rndne_f32_e32 v218, v216
	v_rndne_f32_e32 v225, v223
	v_rndne_f32_e32 v232, v230
	v_rndne_f32_e32 v239, v237
	v_fmac_f32_e32 v217, 0xb2a5705f, v214
	v_fmac_f32_e32 v224, 0xb2a5705f, v221
	v_fmac_f32_e32 v231, 0xb2a5705f, v228
	v_fmac_f32_e32 v238, 0xb2a5705f, v235
	v_sub_f32_e32 v216, v216, v218
	v_sub_f32_e32 v223, v223, v225
	v_sub_f32_e32 v230, v230, v232
	v_sub_f32_e32 v237, v237, v239
	v_add_f32_e32 v216, v216, v217
	v_add_f32_e32 v223, v223, v224
	v_add_f32_e32 v230, v230, v231
	v_add_f32_e32 v237, v237, v238
	v_cvt_i32_f32_e32 v218, v218
	v_cvt_i32_f32_e32 v225, v225
	v_cvt_i32_f32_e32 v232, v232
	v_cvt_i32_f32_e32 v239, v239
	v_exp_f32_e32 v216, v216
	v_exp_f32_e32 v223, v223
	v_exp_f32_e32 v230, v230
	v_exp_f32_e32 v237, v237
	v_cmp_nlt_f32_e64 s[4:5], s20, v214
	v_cmp_nlt_f32_e64 s[98:99], s20, v221
	v_cmp_nlt_f32_e64 s[100:101], s20, v228
	v_cmp_nlt_f32_e64 vcc, s20, v235
	v_ldexp_f32 v216, v216, v218
	v_ldexp_f32 v223, v223, v225
	v_ldexp_f32 v230, v230, v232
	v_ldexp_f32 v237, v237, v239
	v_mul_f32_e32 v215, v213, v213
	v_mul_f32_e32 v222, v220, v220
	v_mul_f32_e32 v229, v227, v227
	v_mul_f32_e32 v236, v234, v234
	v_cndmask_b32_e64 v216, 0, v216, s[4:5]
	v_cndmask_b32_e64 v223, 0, v223, s[98:99]
	v_cndmask_b32_e64 v230, 0, v230, s[100:101]
	v_cndmask_b32_e64 v237, 0, v237, vcc
	v_cmp_ngt_f32_e64 s[4:5], s21, v214
	v_cmp_ngt_f32_e64 s[98:99], s21, v221
	v_cmp_ngt_f32_e64 s[100:101], s21, v228
	v_cmp_ngt_f32_e64 vcc, s21, v235
	v_fmamk_f32 v217, v215, 0xba1345e1, v195
	v_fmamk_f32 v224, v222, 0xba1345e1, v195
	v_fmamk_f32 v231, v229, 0xba1345e1, v195
	v_fmamk_f32 v238, v236, 0xba1345e1, v195
	v_fmaak_f32 v217, v215, v217, 0xbcdac9b8
	v_fmaak_f32 v224, v222, v224, 0xbcdac9b8
	v_fmaak_f32 v231, v229, v231, 0xbcdac9b8
	v_fmaak_f32 v238, v236, v238, 0xbcdac9b8
	v_cndmask_b32_e64 v216, v194, v216, s[4:5]
	v_cndmask_b32_e64 v223, v194, v223, s[98:99]
	v_cndmask_b32_e64 v230, v194, v230, s[100:101]
	v_cndmask_b32_e64 v237, v194, v237, vcc
	v_fmaak_f32 v217, v215, v217, 0x3de703be
	v_fmaak_f32 v224, v222, v224, 0x3de703be
	v_fmaak_f32 v231, v229, v231, 0x3de703be
	v_fmaak_f32 v238, v236, v238, 0x3de703be
	v_fmaak_f32 v217, v215, v217, 0xbec09330
	v_fmaak_f32 v224, v222, v224, 0xbec09330
	v_fmaak_f32 v231, v229, v231, 0xbec09330
	v_fmaak_f32 v238, v236, v238, 0xbec09330
	v_sub_f32_e32 v216, 1.0, v216
	v_sub_f32_e32 v223, 1.0, v223
	v_sub_f32_e32 v230, 1.0, v230
	v_sub_f32_e32 v237, 1.0, v237
	v_fmaak_f32 v217, v215, v217, 0x3e0375d0
	v_fmaak_f32 v224, v222, v224, 0x3e0375d0
	v_fmaak_f32 v231, v229, v231, 0x3e0375d0
	v_fmaak_f32 v238, v236, v238, 0x3e0375d0
	v_cmp_nlt_f32_e64 s[4:5], |v213|, 1.0
	v_cmp_nlt_f32_e64 s[98:99], |v220|, 1.0
	v_cmp_nlt_f32_e64 s[100:101], |v227|, 1.0
	v_cmp_nlt_f32_e64 vcc, |v234|, 1.0
	v_fma_f32 v217, |v213|, v217, |v213|
	v_fma_f32 v224, |v220|, v224, |v220|
	v_fma_f32 v231, |v227|, v231, |v227|
	v_fma_f32 v238, |v234|, v238, |v234|
	v_mul_f32_e32 v212, 0.5, v212
	v_mul_f32_e32 v219, 0.5, v219
	v_mul_f32_e32 v226, 0.5, v226
	v_mul_f32_e32 v233, 0.5, v233
	v_mul_f32_e32 v215, v132, v124
	v_mul_f32_e32 v222, v133, v125
	v_mul_f32_e32 v229, v134, v126
	v_mul_f32_e32 v236, v135, v127
	v_cndmask_b32_e64 v216, v217, v216, s[4:5]
	v_cndmask_b32_e64 v223, v224, v223, s[98:99]
	v_cndmask_b32_e64 v230, v231, v230, s[100:101]
	v_cndmask_b32_e64 v237, v238, v237, vcc
	v_bfi_b32 v216, s22, v216, v213
	v_bfi_b32 v223, s22, v223, v220
	v_bfi_b32 v230, s22, v230, v227
	v_bfi_b32 v237, s22, v237, v234
	v_add_f32_e32 v216, 1.0, v216
	v_add_f32_e32 v223, 1.0, v223
	v_add_f32_e32 v230, 1.0, v230
	v_add_f32_e32 v237, 1.0, v237
	v_mul_f32_e32 v212, v212, v216
	v_mul_f32_e32 v219, v219, v223
	v_mul_f32_e32 v226, v226, v230
	v_mul_f32_e32 v233, v233, v237
	v_mul_f32_e32 v212, v132, v212
	v_mul_f32_e32 v219, v133, v219
	v_mul_f32_e32 v226, v134, v226
	v_mul_f32_e32 v233, v135, v233
	v_mul_f32_e32 v240, v124, v212
	v_mul_f32_e32 v241, v125, v219
	v_mul_f32_e32 v242, v126, v226
	v_mul_f32_e32 v243, v127, v233
	global_store_dwordx4 v250, v[240:243], s[94:95]
	v_add_u32_e32 v250, 0x200000, v250
	s_add_u32 s17, s17, 1
	s_cmp_lt_u32 s17, s16
	s_cbranch_scc0 .Lact0_done
	s_waitcnt vmcnt(24)
	v_lshlrev_b32_e32 v196, 2, v108
	v_lshlrev_b32_e32 v197, 2, v109
	v_lshlrev_b32_e32 v198, 2, v110
	v_lshlrev_b32_e32 v199, 2, v111
	ds_read_b32 v116, v196
	ds_read_b32 v117, v197
	ds_read_b32 v118, v198
	ds_read_b32 v119, v199
	global_load_dword v124, v196, s[26:27]
	global_load_dword v125, v197, s[26:27]
	global_load_dword v126, v198, s[26:27]
	global_load_dword v127, v199, s[26:27]
	global_load_dwordx4 v[132:135], v248, s[94:95]
	v_add_u32_e32 v248, 0x200000, v248
	v_min_u32_e32 v248, v248, v249
	global_load_dwordx4 v[100:103], v246, s[94:95]
	v_add_u32_e32 v246, 0x200000, v246
	v_min_u32_e32 v246, v246, v247
	global_load_dwordx4 v[0:3], v244, s[94:95]
	v_add_u32_e32 v251, 0x2040000, v244
	global_load_dwordx4 v[4:7], v251, s[94:95]
	v_add_u32_e32 v251, 0x4080000, v244
	global_load_dwordx4 v[8:11], v251, s[94:95]
	v_add_u32_e32 v251, 0x60c0000, v244
	global_load_dwordx4 v[12:15], v251, s[94:95]
	v_add_u32_e32 v251, 0x8100000, v244
	global_load_dwordx4 v[16:19], v251, s[94:95]
	v_add_u32_e32 v251, 0xa140000, v244
	global_load_dwordx4 v[20:23], v251, s[94:95]
	v_add_u32_e32 v251, 0xc180000, v244
	global_load_dwordx4 v[24:27], v251, s[94:95]
	v_add_u32_e32 v251, 0xe1c0000, v244
	global_load_dwordx4 v[28:31], v251, s[94:95]
	v_add_u32_e32 v244, 0x200000, v244
	v_min_u32_e32 v244, v244, v245
	s_waitcnt vmcnt(24) lgkmcnt(4)
	v_add_f32_e32 v212, 0, v32
	v_add_f32_e32 v219, 0, v33
	v_add_f32_e32 v226, 0, v34
	v_add_f32_e32 v233, 0, v35
	v_add_f32_e32 v212, v212, v36
	v_add_f32_e32 v219, v219, v37
	v_add_f32_e32 v226, v226, v38
	v_add_f32_e32 v233, v233, v39
	v_add_f32_e32 v212, v212, v40
	v_add_f32_e32 v219, v219, v41
	v_add_f32_e32 v226, v226, v42
	v_add_f32_e32 v233, v233, v43
	v_add_f32_e32 v212, v212, v44
	v_add_f32_e32 v219, v219, v45
	v_add_f32_e32 v226, v226, v46
	v_add_f32_e32 v233, v233, v47
	v_add_f32_e32 v212, v212, v48
	v_add_f32_e32 v219, v219, v49
	v_add_f32_e32 v226, v226, v50
	v_add_f32_e32 v233, v233, v51
	v_add_f32_e32 v212, v212, v52
	v_add_f32_e32 v219, v219, v53
	v_add_f32_e32 v226, v226, v54
	v_add_f32_e32 v233, v233, v55
	v_add_f32_e32 v212, v212, v56
	v_add_f32_e32 v219, v219, v57
	v_add_f32_e32 v226, v226, v58
	v_add_f32_e32 v233, v233, v59
	v_add_f32_e32 v212, v212, v60
	v_add_f32_e32 v219, v219, v61
	v_add_f32_e32 v226, v226, v62
	v_add_f32_e32 v233, v233, v63
	v_mul_f32_e32 v212, v212, v112
	v_mul_f32_e32 v219, v219, v113
	v_mul_f32_e32 v226, v226, v114
	v_mul_f32_e32 v233, v233, v115
	v_mul_f32_e32 v213, 0x3f3504f3, v212
	v_mul_f32_e32 v220, 0x3f3504f3, v219
	v_mul_f32_e32 v227, 0x3f3504f3, v226
	v_mul_f32_e32 v234, 0x3f3504f3, v233
	v_fma_f32 v214, |v213|, v187, v188
	v_fma_f32 v221, |v220|, v187, v188
	v_fma_f32 v228, |v227|, v187, v188
	v_fma_f32 v235, |v234|, v187, v188
	v_fma_f32 v214, |v213|, v214, v189
	v_fma_f32 v221, |v220|, v221, v189
	v_fma_f32 v228, |v227|, v228, v189
	v_fma_f32 v235, |v234|, v235, v189
	v_fma_f32 v214, |v213|, v214, v190
	v_fma_f32 v221, |v220|, v221, v190
	v_fma_f32 v228, |v227|, v228, v190
	v_fma_f32 v235, |v234|, v235, v190
	v_fma_f32 v214, |v213|, v214, v191
	v_fma_f32 v221, |v220|, v221, v191
	v_fma_f32 v228, |v227|, v228, v191
	v_fma_f32 v235, |v234|, v235, v191
	v_fma_f32 v214, |v213|, v214, v192
	v_fma_f32 v221, |v220|, v221, v192
	v_fma_f32 v228, |v227|, v228, v192
	v_fma_f32 v235, |v234|, v235, v192
	v_fma_f32 v214, |v213|, v214, v193
	v_fma_f32 v221, |v220|, v221, v193
	v_fma_f32 v228, |v227|, v228, v193
	v_fma_f32 v235, |v234|, v235, v193
	v_fma_f32 v214, |v213|, v214, |v213|
	v_fma_f32 v221, |v220|, v221, |v220|
	v_fma_f32 v228, |v227|, v228, |v227|
	v_fma_f32 v235, |v234|, v235, |v234|
	v_mul_f32_e32 v216, s19, v214
	v_mul_f32_e32 v223, s19, v221
	v_mul_f32_e32 v230, s19, v228
	v_mul_f32_e32 v237, s19, v235
	v_fma_f32 v217, v214, s19, -v216
	v_fma_f32 v224, v221, s19, -v223
	v_fma_f32 v231, v228, s19, -v230
	v_fma_f32 v238, v235, s19, -v237
	v_rndne_f32_e32 v218, v216
	v_rndne_f32_e32 v225, v223
	v_rndne_f32_e32 v232, v230
	v_rndne_f32_e32 v239, v237
	v_fmac_f32_e32 v217, 0xb2a5705f, v214
	v_fmac_f32_e32 v224, 0xb2a5705f, v221
	v_fmac_f32_e32 v231, 0xb2a5705f, v228
	v_fmac_f32_e32 v238, 0xb2a5705f, v235
	v_sub_f32_e32 v216, v216, v218
	v_sub_f32_e32 v223, v223, v225
	v_sub_f32_e32 v230, v230, v232
	v_sub_f32_e32 v237, v237, v239
	v_add_f32_e32 v216, v216, v217
	v_add_f32_e32 v223, v223, v224
	v_add_f32_e32 v230, v230, v231
	v_add_f32_e32 v237, v237, v238
	v_cvt_i32_f32_e32 v218, v218
	v_cvt_i32_f32_e32 v225, v225
	v_cvt_i32_f32_e32 v232, v232
	v_cvt_i32_f32_e32 v239, v239
	v_exp_f32_e32 v216, v216
	v_exp_f32_e32 v223, v223
	v_exp_f32_e32 v230, v230
	v_exp_f32_e32 v237, v237
	v_cmp_nlt_f32_e64 s[4:5], s20, v214
	v_cmp_nlt_f32_e64 s[98:99], s20, v221
	v_cmp_nlt_f32_e64 s[100:101], s20, v228
	v_cmp_nlt_f32_e64 vcc, s20, v235
	v_ldexp_f32 v216, v216, v218
	v_ldexp_f32 v223, v223, v225
	v_ldexp_f32 v230, v230, v232
	v_ldexp_f32 v237, v237, v239
	v_mul_f32_e32 v215, v213, v213
	v_mul_f32_e32 v222, v220, v220
	v_mul_f32_e32 v229, v227, v227
	v_mul_f32_e32 v236, v234, v234
	v_cndmask_b32_e64 v216, 0, v216, s[4:5]
	v_cndmask_b32_e64 v223, 0, v223, s[98:99]
	v_cndmask_b32_e64 v230, 0, v230, s[100:101]
	v_cndmask_b32_e64 v237, 0, v237, vcc
	v_cmp_ngt_f32_e64 s[4:5], s21, v214
	v_cmp_ngt_f32_e64 s[98:99], s21, v221
	v_cmp_ngt_f32_e64 s[100:101], s21, v228
	v_cmp_ngt_f32_e64 vcc, s21, v235
	v_fmamk_f32 v217, v215, 0xba1345e1, v195
	v_fmamk_f32 v224, v222, 0xba1345e1, v195
	v_fmamk_f32 v231, v229, 0xba1345e1, v195
	v_fmamk_f32 v238, v236, 0xba1345e1, v195
	v_fmaak_f32 v217, v215, v217, 0xbcdac9b8
	v_fmaak_f32 v224, v222, v224, 0xbcdac9b8
	v_fmaak_f32 v231, v229, v231, 0xbcdac9b8
	v_fmaak_f32 v238, v236, v238, 0xbcdac9b8
	v_cndmask_b32_e64 v216, v194, v216, s[4:5]
	v_cndmask_b32_e64 v223, v194, v223, s[98:99]
	v_cndmask_b32_e64 v230, v194, v230, s[100:101]
	v_cndmask_b32_e64 v237, v194, v237, vcc
	v_fmaak_f32 v217, v215, v217, 0x3de703be
	v_fmaak_f32 v224, v222, v224, 0x3de703be
	v_fmaak_f32 v231, v229, v231, 0x3de703be
	v_fmaak_f32 v238, v236, v238, 0x3de703be
	v_fmaak_f32 v217, v215, v217, 0xbec09330
	v_fmaak_f32 v224, v222, v224, 0xbec09330
	v_fmaak_f32 v231, v229, v231, 0xbec09330
	v_fmaak_f32 v238, v236, v238, 0xbec09330
	v_sub_f32_e32 v216, 1.0, v216
	v_sub_f32_e32 v223, 1.0, v223
	v_sub_f32_e32 v230, 1.0, v230
	v_sub_f32_e32 v237, 1.0, v237
	v_fmaak_f32 v217, v215, v217, 0x3e0375d0
	v_fmaak_f32 v224, v222, v224, 0x3e0375d0
	v_fmaak_f32 v231, v229, v231, 0x3e0375d0
	v_fmaak_f32 v238, v236, v238, 0x3e0375d0
	v_cmp_nlt_f32_e64 s[4:5], |v213|, 1.0
	v_cmp_nlt_f32_e64 s[98:99], |v220|, 1.0
	v_cmp_nlt_f32_e64 s[100:101], |v227|, 1.0
	v_cmp_nlt_f32_e64 vcc, |v234|, 1.0
	v_fma_f32 v217, |v213|, v217, |v213|
	v_fma_f32 v224, |v220|, v224, |v220|
	v_fma_f32 v231, |v227|, v231, |v227|
	v_fma_f32 v238, |v234|, v238, |v234|
	v_mul_f32_e32 v212, 0.5, v212
	v_mul_f32_e32 v219, 0.5, v219
	v_mul_f32_e32 v226, 0.5, v226
	v_mul_f32_e32 v233, 0.5, v233
	v_mul_f32_e32 v215, v128, v120
	v_mul_f32_e32 v222, v129, v121
	v_mul_f32_e32 v229, v130, v122
	v_mul_f32_e32 v236, v131, v123
	v_cndmask_b32_e64 v216, v217, v216, s[4:5]
	v_cndmask_b32_e64 v223, v224, v223, s[98:99]
	v_cndmask_b32_e64 v230, v231, v230, s[100:101]
	v_cndmask_b32_e64 v237, v238, v237, vcc
	v_bfi_b32 v216, s22, v216, v213
	v_bfi_b32 v223, s22, v223, v220
	v_bfi_b32 v230, s22, v230, v227
	v_bfi_b32 v237, s22, v237, v234
	v_add_f32_e32 v216, 1.0, v216
	v_add_f32_e32 v223, 1.0, v223
	v_add_f32_e32 v230, 1.0, v230
	v_add_f32_e32 v237, 1.0, v237
	v_mul_f32_e32 v212, v212, v216
	v_mul_f32_e32 v219, v219, v223
	v_mul_f32_e32 v226, v226, v230
	v_mul_f32_e32 v233, v233, v237
	v_mul_f32_e32 v212, v128, v212
	v_mul_f32_e32 v219, v129, v219
	v_mul_f32_e32 v226, v130, v226
	v_mul_f32_e32 v233, v131, v233
	v_mul_f32_e32 v240, v120, v212
	v_mul_f32_e32 v241, v121, v219
	v_mul_f32_e32 v242, v122, v226
	v_mul_f32_e32 v243, v123, v233
	global_store_dwordx4 v250, v[240:243], s[94:95]
	v_add_u32_e32 v250, 0x200000, v250
	s_add_u32 s17, s17, 1
	s_cmp_lt_u32 s17, s16
	s_cbranch_scc0 .Lact0_done
	s_waitcnt vmcnt(24)
	v_lshlrev_b32_e32 v196, 2, v96
	v_lshlrev_b32_e32 v197, 2, v97
	v_lshlrev_b32_e32 v198, 2, v98
	v_lshlrev_b32_e32 v199, 2, v99
	ds_read_b32 v112, v196
	ds_read_b32 v113, v197
	ds_read_b32 v114, v198
	ds_read_b32 v115, v199
	global_load_dword v120, v196, s[26:27]
	global_load_dword v121, v197, s[26:27]
	global_load_dword v122, v198, s[26:27]
	global_load_dword v123, v199, s[26:27]
	global_load_dwordx4 v[128:131], v248, s[94:95]
	v_add_u32_e32 v248, 0x200000, v248
	v_min_u32_e32 v248, v248, v249
	global_load_dwordx4 v[104:107], v246, s[94:95]
	v_add_u32_e32 v246, 0x200000, v246
	v_min_u32_e32 v246, v246, v247
	global_load_dwordx4 v[32:35], v244, s[94:95]
	v_add_u32_e32 v251, 0x2040000, v244
	global_load_dwordx4 v[36:39], v251, s[94:95]
	v_add_u32_e32 v251, 0x4080000, v244
	global_load_dwordx4 v[40:43], v251, s[94:95]
	v_add_u32_e32 v251, 0x60c0000, v244
	global_load_dwordx4 v[44:47], v251, s[94:95]
	v_add_u32_e32 v251, 0x8100000, v244
	global_load_dwordx4 v[48:51], v251, s[94:95]
	v_add_u32_e32 v251, 0xa140000, v244
	global_load_dwordx4 v[52:55], v251, s[94:95]
	v_add_u32_e32 v251, 0xc180000, v244
	global_load_dwordx4 v[56:59], v251, s[94:95]
	v_add_u32_e32 v251, 0xe1c0000, v244
	global_load_dwordx4 v[60:63], v251, s[94:95]
	v_add_u32_e32 v244, 0x200000, v244
	v_min_u32_e32 v244, v244, v245
	s_waitcnt vmcnt(24) lgkmcnt(4)
	v_add_f32_e32 v212, 0, v64
	v_add_f32_e32 v219, 0, v65
	v_add_f32_e32 v226, 0, v66
	v_add_f32_e32 v233, 0, v67
	v_add_f32_e32 v212, v212, v68
	v_add_f32_e32 v219, v219, v69
	v_add_f32_e32 v226, v226, v70
	v_add_f32_e32 v233, v233, v71
	v_add_f32_e32 v212, v212, v72
	v_add_f32_e32 v219, v219, v73
	v_add_f32_e32 v226, v226, v74
	v_add_f32_e32 v233, v233, v75
	v_add_f32_e32 v212, v212, v76
	v_add_f32_e32 v219, v219, v77
	v_add_f32_e32 v226, v226, v78
	v_add_f32_e32 v233, v233, v79
	v_add_f32_e32 v212, v212, v80
	v_add_f32_e32 v219, v219, v81
	v_add_f32_e32 v226, v226, v82
	v_add_f32_e32 v233, v233, v83
	v_add_f32_e32 v212, v212, v84
	v_add_f32_e32 v219, v219, v85
	v_add_f32_e32 v226, v226, v86
	v_add_f32_e32 v233, v233, v87
	v_add_f32_e32 v212, v212, v88
	v_add_f32_e32 v219, v219, v89
	v_add_f32_e32 v226, v226, v90
	v_add_f32_e32 v233, v233, v91
	v_add_f32_e32 v212, v212, v92
	v_add_f32_e32 v219, v219, v93
	v_add_f32_e32 v226, v226, v94
	v_add_f32_e32 v233, v233, v95
	v_mul_f32_e32 v212, v212, v116
	v_mul_f32_e32 v219, v219, v117
	v_mul_f32_e32 v226, v226, v118
	v_mul_f32_e32 v233, v233, v119
	v_mul_f32_e32 v213, 0x3f3504f3, v212
	v_mul_f32_e32 v220, 0x3f3504f3, v219
	v_mul_f32_e32 v227, 0x3f3504f3, v226
	v_mul_f32_e32 v234, 0x3f3504f3, v233
	v_fma_f32 v214, |v213|, v187, v188
	v_fma_f32 v221, |v220|, v187, v188
	v_fma_f32 v228, |v227|, v187, v188
	v_fma_f32 v235, |v234|, v187, v188
	v_fma_f32 v214, |v213|, v214, v189
	v_fma_f32 v221, |v220|, v221, v189
	v_fma_f32 v228, |v227|, v228, v189
	v_fma_f32 v235, |v234|, v235, v189
	v_fma_f32 v214, |v213|, v214, v190
	v_fma_f32 v221, |v220|, v221, v190
	v_fma_f32 v228, |v227|, v228, v190
	v_fma_f32 v235, |v234|, v235, v190
	v_fma_f32 v214, |v213|, v214, v191
	v_fma_f32 v221, |v220|, v221, v191
	v_fma_f32 v228, |v227|, v228, v191
	v_fma_f32 v235, |v234|, v235, v191
	v_fma_f32 v214, |v213|, v214, v192
	v_fma_f32 v221, |v220|, v221, v192
	v_fma_f32 v228, |v227|, v228, v192
	v_fma_f32 v235, |v234|, v235, v192
	v_fma_f32 v214, |v213|, v214, v193
	v_fma_f32 v221, |v220|, v221, v193
	v_fma_f32 v228, |v227|, v228, v193
	v_fma_f32 v235, |v234|, v235, v193
	v_fma_f32 v214, |v213|, v214, |v213|
	v_fma_f32 v221, |v220|, v221, |v220|
	v_fma_f32 v228, |v227|, v228, |v227|
	v_fma_f32 v235, |v234|, v235, |v234|
	v_mul_f32_e32 v216, s19, v214
	v_mul_f32_e32 v223, s19, v221
	v_mul_f32_e32 v230, s19, v228
	v_mul_f32_e32 v237, s19, v235
	v_fma_f32 v217, v214, s19, -v216
	v_fma_f32 v224, v221, s19, -v223
	v_fma_f32 v231, v228, s19, -v230
	v_fma_f32 v238, v235, s19, -v237
	v_rndne_f32_e32 v218, v216
	v_rndne_f32_e32 v225, v223
	v_rndne_f32_e32 v232, v230
	v_rndne_f32_e32 v239, v237
	v_fmac_f32_e32 v217, 0xb2a5705f, v214
	v_fmac_f32_e32 v224, 0xb2a5705f, v221
	v_fmac_f32_e32 v231, 0xb2a5705f, v228
	v_fmac_f32_e32 v238, 0xb2a5705f, v235
	v_sub_f32_e32 v216, v216, v218
	v_sub_f32_e32 v223, v223, v225
	v_sub_f32_e32 v230, v230, v232
	v_sub_f32_e32 v237, v237, v239
	v_add_f32_e32 v216, v216, v217
	v_add_f32_e32 v223, v223, v224
	v_add_f32_e32 v230, v230, v231
	v_add_f32_e32 v237, v237, v238
	v_cvt_i32_f32_e32 v218, v218
	v_cvt_i32_f32_e32 v225, v225
	v_cvt_i32_f32_e32 v232, v232
	v_cvt_i32_f32_e32 v239, v239
	v_exp_f32_e32 v216, v216
	v_exp_f32_e32 v223, v223
	v_exp_f32_e32 v230, v230
	v_exp_f32_e32 v237, v237
	v_cmp_nlt_f32_e64 s[4:5], s20, v214
	v_cmp_nlt_f32_e64 s[98:99], s20, v221
	v_cmp_nlt_f32_e64 s[100:101], s20, v228
	v_cmp_nlt_f32_e64 vcc, s20, v235
	v_ldexp_f32 v216, v216, v218
	v_ldexp_f32 v223, v223, v225
	v_ldexp_f32 v230, v230, v232
	v_ldexp_f32 v237, v237, v239
	v_mul_f32_e32 v215, v213, v213
	v_mul_f32_e32 v222, v220, v220
	v_mul_f32_e32 v229, v227, v227
	v_mul_f32_e32 v236, v234, v234
	v_cndmask_b32_e64 v216, 0, v216, s[4:5]
	v_cndmask_b32_e64 v223, 0, v223, s[98:99]
	v_cndmask_b32_e64 v230, 0, v230, s[100:101]
	v_cndmask_b32_e64 v237, 0, v237, vcc
	v_cmp_ngt_f32_e64 s[4:5], s21, v214
	v_cmp_ngt_f32_e64 s[98:99], s21, v221
	v_cmp_ngt_f32_e64 s[100:101], s21, v228
	v_cmp_ngt_f32_e64 vcc, s21, v235
	v_fmamk_f32 v217, v215, 0xba1345e1, v195
	v_fmamk_f32 v224, v222, 0xba1345e1, v195
	v_fmamk_f32 v231, v229, 0xba1345e1, v195
	v_fmamk_f32 v238, v236, 0xba1345e1, v195
	v_fmaak_f32 v217, v215, v217, 0xbcdac9b8
	v_fmaak_f32 v224, v222, v224, 0xbcdac9b8
	v_fmaak_f32 v231, v229, v231, 0xbcdac9b8
	v_fmaak_f32 v238, v236, v238, 0xbcdac9b8
	v_cndmask_b32_e64 v216, v194, v216, s[4:5]
	v_cndmask_b32_e64 v223, v194, v223, s[98:99]
	v_cndmask_b32_e64 v230, v194, v230, s[100:101]
	v_cndmask_b32_e64 v237, v194, v237, vcc
	v_fmaak_f32 v217, v215, v217, 0x3de703be
	v_fmaak_f32 v224, v222, v224, 0x3de703be
	v_fmaak_f32 v231, v229, v231, 0x3de703be
	v_fmaak_f32 v238, v236, v238, 0x3de703be
	v_fmaak_f32 v217, v215, v217, 0xbec09330
	v_fmaak_f32 v224, v222, v224, 0xbec09330
	v_fmaak_f32 v231, v229, v231, 0xbec09330
	v_fmaak_f32 v238, v236, v238, 0xbec09330
	v_sub_f32_e32 v216, 1.0, v216
	v_sub_f32_e32 v223, 1.0, v223
	v_sub_f32_e32 v230, 1.0, v230
	v_sub_f32_e32 v237, 1.0, v237
	v_fmaak_f32 v217, v215, v217, 0x3e0375d0
	v_fmaak_f32 v224, v222, v224, 0x3e0375d0
	v_fmaak_f32 v231, v229, v231, 0x3e0375d0
	v_fmaak_f32 v238, v236, v238, 0x3e0375d0
	v_cmp_nlt_f32_e64 s[4:5], |v213|, 1.0
	v_cmp_nlt_f32_e64 s[98:99], |v220|, 1.0
	v_cmp_nlt_f32_e64 s[100:101], |v227|, 1.0
	v_cmp_nlt_f32_e64 vcc, |v234|, 1.0
	v_fma_f32 v217, |v213|, v217, |v213|
	v_fma_f32 v224, |v220|, v224, |v220|
	v_fma_f32 v231, |v227|, v231, |v227|
	v_fma_f32 v238, |v234|, v238, |v234|
	v_mul_f32_e32 v212, 0.5, v212
	v_mul_f32_e32 v219, 0.5, v219
	v_mul_f32_e32 v226, 0.5, v226
	v_mul_f32_e32 v233, 0.5, v233
	v_mul_f32_e32 v215, v132, v124
	v_mul_f32_e32 v222, v133, v125
	v_mul_f32_e32 v229, v134, v126
	v_mul_f32_e32 v236, v135, v127
	v_cndmask_b32_e64 v216, v217, v216, s[4:5]
	v_cndmask_b32_e64 v223, v224, v223, s[98:99]
	v_cndmask_b32_e64 v230, v231, v230, s[100:101]
	v_cndmask_b32_e64 v237, v238, v237, vcc
	v_bfi_b32 v216, s22, v216, v213
	v_bfi_b32 v223, s22, v223, v220
	v_bfi_b32 v230, s22, v230, v227
	v_bfi_b32 v237, s22, v237, v234
	v_add_f32_e32 v216, 1.0, v216
	v_add_f32_e32 v223, 1.0, v223
	v_add_f32_e32 v230, 1.0, v230
	v_add_f32_e32 v237, 1.0, v237
	v_mul_f32_e32 v212, v212, v216
	v_mul_f32_e32 v219, v219, v223
	v_mul_f32_e32 v226, v226, v230
	v_mul_f32_e32 v233, v233, v237
	v_mul_f32_e32 v212, v132, v212
	v_mul_f32_e32 v219, v133, v219
	v_mul_f32_e32 v226, v134, v226
	v_mul_f32_e32 v233, v135, v233
	v_mul_f32_e32 v240, v124, v212
	v_mul_f32_e32 v241, v125, v219
	v_mul_f32_e32 v242, v126, v226
	v_mul_f32_e32 v243, v127, v233
	global_store_dwordx4 v250, v[240:243], s[94:95]
	v_add_u32_e32 v250, 0x200000, v250
	s_add_u32 s17, s17, 1
	s_cmp_lt_u32 s17, s16
	s_cbranch_scc1 .Lact0_loop
.Lact0_done:
	s_waitcnt vmcnt(0) lgkmcnt(0)
	s_barrier
.LBB0_673:
	s_or_b64 exec, exec, s[2:3]
	s_waitcnt vmcnt(0) lgkmcnt(0)
	s_barrier
	s_mov_b64 s[2:3], exec
	v_readlane_b32 s4, v252, 31
	v_readlane_b32 s5, v252, 32
	s_and_b64 s[4:5], s[2:3], s[4:5]
	s_mov_b64 exec, s[4:5]
	s_cbranch_execz .LBB0_679
	s_mov_b64 s[4:5], exec
	buffer_wbl2 sc1
	s_waitcnt vmcnt(0)
	s_waitcnt vmcnt(0)
	v_mbcnt_lo_u32_b32 v0, s4, 0
	v_mbcnt_hi_u32_b32 v0, s5, v0
	v_cmp_eq_u32_e32 vcc, 0, v0
	s_and_saveexec_b64 s[16:17], vcc
	s_cbranch_execz .LBB0_676
	s_bcnt1_i32_b64 s4, s[4:5]
	s_and_b32 s98, s88, 7
	s_lshl_b32 s98, s98, 8
	s_add_u32 s98, s98, 0x3c6f0000
	v_mov_b32_e32 v0, s98
	v_mov_b32_e32 v1, s4
	global_atomic_add v1, v0, v1, s[94:95] sc0

.LBB0_1116:
	s_or_b64 exec, exec, s[0:1]
	s_barrier
	s_and_saveexec_b64 s[0:1], s[14:15]
	s_cbranch_execz .LBB0_1135
	s_add_u32 s24, s94, 0x3a700000
	s_addc_u32 s25, s95, 0
	s_add_u32 s26, s94, 0x3a710000
	s_addc_u32 s27, s95, 0
	v_lshlrev_b32_e32 v251, 4, v156
	v_add_u32_e32 v244, 0x0, v251
	global_load_dwordx4 v[0:3], v244, s[24:25]
	v_add_u32_e32 v244, 0x1000, v251
	global_load_dwordx4 v[4:7], v244, s[24:25]
	v_add_u32_e32 v244, 0x2000, v251
	global_load_dwordx4 v[8:11], v244, s[24:25]
	v_add_u32_e32 v244, 0x3000, v251
	global_load_dwordx4 v[12:15], v244, s[24:25]
	v_add_u32_e32 v244, 0x4000, v251
	global_load_dwordx4 v[16:19], v244, s[24:25]
	v_add_u32_e32 v244, 0x5000, v251
	global_load_dwordx4 v[20:23], v244, s[24:25]
	v_add_u32_e32 v244, 0x6000, v251
	global_load_dwordx4 v[24:27], v244, s[24:25]
	v_add_u32_e32 v244, 0x7000, v251
	global_load_dwordx4 v[28:31], v244, s[24:25]
	s_waitcnt vmcnt(0)
	ds_write_b128 v251, v[0:3] offset:0
	ds_write_b128 v251, v[4:7] offset:4096
	ds_write_b128 v251, v[8:11] offset:8192
	ds_write_b128 v251, v[12:15] offset:12288
	ds_write_b128 v251, v[16:19] offset:16384
	ds_write_b128 v251, v[20:23] offset:20480
	ds_write_b128 v251, v[24:27] offset:24576
	ds_write_b128 v251, v[28:31] offset:28672
	v_add_u32_e32 v244, 0x8000, v251
	global_load_dwordx4 v[0:3], v244, s[24:25]
	v_add_u32_e32 v244, 0x9000, v251
	global_load_dwordx4 v[4:7], v244, s[24:25]
	v_add_u32_e32 v244, 0xa000, v251
	global_load_dwordx4 v[8:11], v244, s[24:25]
	v_add_u32_e32 v244, 0xb000, v251
	global_load_dwordx4 v[12:15], v244, s[24:25]
	v_add_u32_e32 v244, 0xc000, v251
	global_load_dwordx4 v[16:19], v244, s[24:25]
	v_add_u32_e32 v244, 0xd000, v251
	global_load_dwordx4 v[20:23], v244, s[24:25]
	v_add_u32_e32 v244, 0xe000, v251
	global_load_dwordx4 v[24:27], v244, s[24:25]
	v_add_u32_e32 v244, 0xf000, v251
	global_load_dwordx4 v[28:31], v244, s[24:25]
	s_waitcnt vmcnt(0)
	ds_write_b128 v251, v[0:3] offset:32768
	ds_write_b128 v251, v[4:7] offset:36864
	ds_write_b128 v251, v[8:11] offset:40960
	ds_write_b128 v251, v[12:15] offset:45056
	ds_write_b128 v251, v[16:19] offset:49152
	ds_write_b128 v251, v[20:23] offset:53248
	ds_write_b128 v251, v[24:27] offset:57344
	ds_write_b128 v251, v[28:31] offset:61440
	s_waitcnt lgkmcnt(0)
	s_barrier
	s_mov_b32 s16, 16
	s_cmp_lt_u32 s88, 64
	s_cselect_b32 s16, 17, 16
	s_lshl_b32 s4, s88, 12
	v_lshlrev_b32_e32 v244, 4, v156
	v_add_u32_e32 v244, s4, v244
	s_sub_u32 s4, s16, 1
	s_lshl_b32 s4, s4, 21
	v_add_u32_e32 v245, s4, v244
	v_add_u32_e32 v249, 0x1a340000, v245
	v_add_u32_e32 v247, 0x18300000, v245
	v_add_u32_e32 v245, 0x8100000, v245
	v_add_u32_e32 v248, 0x1a340000, v244
	v_mov_b32_e32 v250, v248
	v_add_u32_e32 v246, 0x18300000, v244
	v_add_u32_e32 v244, 0x8100000, v244
	v_mov_b32_e32 v187, 0x378e98ab
	v_mov_b32_e32 v188, 0xb9c68948
	v_mov_b32_e32 v189, 0x3b7cd369
	v_mov_b32_e32 v190, 0xbcc618b2
	v_mov_b32_e32 v191, 0x3dda74e4
	v_mov_b32_e32 v192, 0x3f228afd
	v_mov_b32_e32 v193, 0x3e03c728
	v_mov_b32_e32 v194, 0x7f800000
	v_mov_b32_e32 v195, 0x3ba10414
	s_mov_b32 s19, 0xbfb8aa3b
	s_mov_b32 s20, 0x42ce8ed0
	s_mov_b32 s21, 0xc2b17218
	s_brev_b32 s22, -2
	global_load_dwordx4 v[96:99], v246, s[94:95]
	v_add_u32_e32 v246, 0x200000, v246
	v_min_u32_e32 v246, v246, v247
	global_load_dwordx4 v[100:103], v246, s[94:95]
	v_add_u32_e32 v246, 0x200000, v246
	v_min_u32_e32 v246, v246, v247
	global_load_dwordx4 v[104:107], v246, s[94:95]
	v_add_u32_e32 v246, 0x200000, v246
	v_min_u32_e32 v246, v246, v247
	global_load_dwordx4 v[0:3], v244, s[94:95]
	v_add_u32_e32 v251, 0x2040000, v244
	global_load_dwordx4 v[4:7], v251, s[94:95]
	v_add_u32_e32 v251, 0x4080000, v244
	global_load_dwordx4 v[8:11], v251, s[94:95]
	v_add_u32_e32 v251, 0x60c0000, v244
	global_load_dwordx4 v[12:15], v251, s[94:95]
	v_add_u32_e32 v251, 0x8100000, v244
	global_load_dwordx4 v[16:19], v251, s[94:95]
	v_add_u32_e32 v251, 0xa140000, v244
	global_load_dwordx4 v[20:23], v251, s[94:95]
	v_add_u32_e32 v251, 0xc180000, v244
	global_load_dwordx4 v[24:27], v251, s[94:95]
	v_add_u32_e32 v251, 0xe1c0000, v244
	global_load_dwordx4 v[28:31], v251, s[94:95]
	v_add_u32_e32 v244, 0x200000, v244
	v_min_u32_e32 v244, v244, v245
	global_load_dwordx4 v[32:35], v244, s[94:95]
	v_add_u32_e32 v251, 0x2040000, v244
	global_load_dwordx4 v[36:39], v251, s[94:95]
	v_add_u32_e32 v251, 0x4080000, v244
	global_load_dwordx4 v[40:43], v251, s[94:95]
	v_add_u32_e32 v251, 0x60c0000, v244
	global_load_dwordx4 v[44:47], v251, s[94:95]
	v_add_u32_e32 v251, 0x8100000, v244
	global_load_dwordx4 v[48:51], v251, s[94:95]
	v_add_u32_e32 v251, 0xa140000, v244
	global_load_dwordx4 v[52:55], v251, s[94:95]
	v_add_u32_e32 v251, 0xc180000, v244
	global_load_dwordx4 v[56:59], v251, s[94:95]
	v_add_u32_e32 v251, 0xe1c0000, v244
	global_load_dwordx4 v[60:63], v251, s[94:95]
	v_add_u32_e32 v244, 0x200000, v244
	v_min_u32_e32 v244, v244, v245
	s_waitcnt vmcnt(18)
	v_lshlrev_b32_e32 v196, 2, v96
	v_lshlrev_b32_e32 v197, 2, v97
	v_lshlrev_b32_e32 v198, 2, v98
	v_lshlrev_b32_e32 v199, 2, v99
	ds_read_b32 v112, v196
	ds_read_b32 v113, v197
	ds_read_b32 v114, v198
	ds_read_b32 v115, v199
	global_load_dword v120, v196, s[26:27]
	global_load_dword v121, v197, s[26:27]
	global_load_dword v122, v198, s[26:27]
	global_load_dword v123, v199, s[26:27]
	global_load_dwordx4 v[128:131], v248, s[94:95]
	v_add_u32_e32 v248, 0x200000, v248
	v_min_u32_e32 v248, v248, v249
	s_waitcnt vmcnt(5)
	global_load_dword v200, v250, s[94:95]
	global_load_dword v200, v250, s[94:95]
	global_load_dword v200, v250, s[94:95]
	global_load_dword v200, v250, s[94:95]
	global_load_dword v200, v250, s[94:95]
	global_load_dword v200, v250, s[94:95]
	global_load_dword v200, v250, s[94:95]
	global_load_dword v200, v250, s[94:95]
	global_load_dword v200, v250, s[94:95]
	global_load_dword v200, v250, s[94:95]
	s_mov_b32 s17, 0

.Lact1_done:
	s_waitcnt vmcnt(0) lgkmcnt(0)
	s_barrier
.LBB0_1135:
	s_or_b64 exec, exec, s[0:1]
	s_waitcnt vmcnt(0) lgkmcnt(0)
	s_barrier
	s_mov_b64 s[0:1], exec
	v_readlane_b32 s2, v252, 31
	v_readlane_b32 s3, v252, 32
	s_and_b64 s[2:3], s[0:1], s[2:3]
	s_mov_b64 exec, s[2:3]
	s_cbranch_execz .LBB0_1141
	s_mov_b64 s[2:3], exec
	buffer_wbl2 sc1
	s_waitcnt vmcnt(0)
	s_waitcnt vmcnt(0)
	v_mbcnt_lo_u32_b32 v0, s2, 0
	v_mbcnt_hi_u32_b32 v0, s3, v0
	v_cmp_eq_u32_e32 vcc, 0, v0
	s_and_saveexec_b64 s[4:5], vcc
	s_cbranch_execz .LBB0_1138
	s_bcnt1_i32_b64 s2, s[2:3]
	s_and_b32 s98, s88, 7
	s_lshl_b32 s98, s98, 8
	s_add_u32 s98, s98, 0x3c6f0000
	v_mov_b32_e32 v0, s98
	v_mov_b32_e32 v1, s2
	global_atomic_add v1, v0, v1, s[94:95] sc0
